# v96 + static priority raise by role: mLSTM output items run at s_setprio 1/2, the co-resident G2b GEMM tiles at 0/1
# baseline (speedup 1.0000x reference)
.LBB1_99:
	v_mul_f32_e32 v116, v33, v35
	v_cvt_pk_bf16_f32 v32, v32, v36
	v_cvt_pk_bf16_f32 v33, v41, v38
	ds_write_b64 v43, v[32:33] offset:4576
	v_add_u32_e32 v56, v158, v42
	v_mul_f32_e32 v110, v45, v47
	v_mul_f32_e32 v114, v44, v46
	v_mul_f32_e32 v112, v34, v37
	s_waitcnt lgkmcnt(0)
	s_barrier
	ds_read_b128 v[32:35], v56
	ds_read_b128 v[36:39], v56 offset:64
	ds_read_b128 v[40:43], v56 offset:128
	ds_read_b128 v[88:91], v56 offset:192
	ds_read_b128 v[44:47], v56 offset:4352
	ds_read_b128 v[48:51], v56 offset:4416
	ds_read_b128 v[52:55], v56 offset:4480
	ds_read_b128 v[92:95], v56 offset:4544
	ds_read_b128 v[56:59], v157 offset:34816
	ds_read_b128 v[60:63], v157 offset:39168
	ds_read_b128 v[64:67], v157 offset:43520
	ds_read_b128 v[68:71], v157 offset:47872
	ds_read_b128 v[72:75], v157 offset:52224
	ds_read_b128 v[76:79], v157 offset:56576
	ds_read_b128 v[80:83], v157 offset:60928
	ds_read_b128 v[84:87], v157 offset:65280
	s_setprio 2
	s_waitcnt lgkmcnt(7)
	v_mfma_f32_16x16x32_bf16 v[96:99], v[56:59], v[32:35], 0
	v_mfma_f32_16x16x32_bf16 v[56:59], v[56:59], v[44:47], 0
	s_waitcnt lgkmcnt(6)
	v_mfma_f32_16x16x32_bf16 v[100:103], v[60:63], v[32:35], 0
	v_mfma_f32_16x16x32_bf16 v[60:63], v[60:63], v[44:47], 0
	s_waitcnt lgkmcnt(5)
	v_mfma_f32_16x16x32_bf16 v[118:121], v[64:67], v[32:35], 0
	v_mfma_f32_16x16x32_bf16 v[64:67], v[64:67], v[44:47], 0
	s_waitcnt lgkmcnt(4)
	v_mfma_f32_16x16x32_bf16 v[122:125], v[68:71], v[32:35], 0
	v_mfma_f32_16x16x32_bf16 v[68:71], v[68:71], v[44:47], 0
	s_waitcnt lgkmcnt(3)
	v_mfma_f32_16x16x32_bf16 v[130:133], v[72:75], v[32:35], 0
	v_mfma_f32_16x16x32_bf16 v[72:75], v[72:75], v[44:47], 0
	s_waitcnt lgkmcnt(2)
	v_mfma_f32_16x16x32_bf16 v[134:137], v[76:79], v[32:35], 0
	v_mfma_f32_16x16x32_bf16 v[76:79], v[76:79], v[44:47], 0
	s_waitcnt lgkmcnt(1)
	v_mfma_f32_16x16x32_bf16 v[138:141], v[80:83], v[32:35], 0
	v_mfma_f32_16x16x32_bf16 v[80:83], v[80:83], v[44:47], 0
	s_waitcnt lgkmcnt(0)
	v_mfma_f32_16x16x32_bf16 v[32:35], v[84:87], v[32:35], 0
	v_mfma_f32_16x16x32_bf16 v[44:47], v[84:87], v[44:47], 0
	s_setprio 1
	ds_read_b128 v[84:87], v157 offset:34880
	ds_read_b128 v[142:145], v157 offset:39232
	ds_read_b128 v[146:149], v157 offset:43584
	ds_read_b128 v[150:153], v157 offset:47936
	ds_read_b128 v[158:161], v157 offset:52288
	ds_read_b128 v[188:191], v157 offset:56640
	ds_read_b128 v[192:195], v157 offset:60992
	ds_read_b128 v[196:199], v157 offset:65344
	s_setprio 2
	s_waitcnt lgkmcnt(7)
	v_mfma_f32_16x16x32_bf16 v[96:99], v[84:87], v[36:39], v[96:99]
	v_mfma_f32_16x16x32_bf16 v[56:59], v[84:87], v[48:51], v[56:59]
	s_waitcnt lgkmcnt(6)
	v_mfma_f32_16x16x32_bf16 v[84:87], v[142:145], v[36:39], v[100:103]
	v_mfma_f32_16x16x32_bf16 v[60:63], v[142:145], v[48:51], v[60:63]
	s_waitcnt lgkmcnt(5)
	v_mfma_f32_16x16x32_bf16 v[100:103], v[146:149], v[36:39], v[118:121]
	v_mfma_f32_16x16x32_bf16 v[64:67], v[146:149], v[48:51], v[64:67]
	s_waitcnt lgkmcnt(4)
	v_mfma_f32_16x16x32_bf16 v[118:121], v[150:153], v[36:39], v[122:125]
	v_mfma_f32_16x16x32_bf16 v[68:71], v[150:153], v[48:51], v[68:71]
	s_waitcnt lgkmcnt(3)
	v_mfma_f32_16x16x32_bf16 v[122:125], v[158:161], v[36:39], v[130:133]
	v_mfma_f32_16x16x32_bf16 v[72:75], v[158:161], v[48:51], v[72:75]
	s_waitcnt lgkmcnt(2)
	v_mfma_f32_16x16x32_bf16 v[130:133], v[188:191], v[36:39], v[134:137]
	v_mfma_f32_16x16x32_bf16 v[76:79], v[188:191], v[48:51], v[76:79]
	s_waitcnt lgkmcnt(1)
	v_mfma_f32_16x16x32_bf16 v[134:137], v[192:195], v[36:39], v[138:141]
	v_mfma_f32_16x16x32_bf16 v[80:83], v[192:195], v[48:51], v[80:83]
	s_waitcnt lgkmcnt(0)
	v_mfma_f32_16x16x32_bf16 v[32:35], v[196:199], v[36:39], v[32:35]
	v_mfma_f32_16x16x32_bf16 v[36:39], v[196:199], v[48:51], v[44:47]
	s_setprio 1
	s_nop 1
	ds_read_b128 v[44:47], v157 offset:34944
	ds_read_b128 v[48:51], v157 offset:39296
	ds_read_b128 v[138:141], v157 offset:43648
	ds_read_b128 v[142:145], v157 offset:48000
	ds_read_b128 v[146:149], v157 offset:52352
	ds_read_b128 v[150:153], v157 offset:56704
	ds_read_b128 v[158:161], v157 offset:61056
	ds_read_b128 v[188:191], v157 offset:65408
	s_setprio 2
	s_waitcnt lgkmcnt(7)
	v_mfma_f32_16x16x32_bf16 v[96:99], v[44:47], v[40:43], v[96:99]
	v_mfma_f32_16x16x32_bf16 v[44:47], v[44:47], v[52:55], v[56:59]
	s_waitcnt lgkmcnt(6)
	v_mfma_f32_16x16x32_bf16 v[56:59], v[48:51], v[40:43], v[84:87]
	v_mfma_f32_16x16x32_bf16 v[48:51], v[48:51], v[52:55], v[60:63]
	s_waitcnt lgkmcnt(5)
	v_mfma_f32_16x16x32_bf16 v[60:63], v[138:141], v[40:43], v[100:103]
	v_mfma_f32_16x16x32_bf16 v[64:67], v[138:141], v[52:55], v[64:67]
	s_waitcnt lgkmcnt(4)
	v_mfma_f32_16x16x32_bf16 v[84:87], v[142:145], v[40:43], v[118:121]
	v_mfma_f32_16x16x32_bf16 v[68:71], v[142:145], v[52:55], v[68:71]
	s_waitcnt lgkmcnt(3)
	v_mfma_f32_16x16x32_bf16 v[100:103], v[146:149], v[40:43], v[122:125]
	v_mfma_f32_16x16x32_bf16 v[72:75], v[146:149], v[52:55], v[72:75]
	s_waitcnt lgkmcnt(2)
	v_mfma_f32_16x16x32_bf16 v[118:121], v[150:153], v[40:43], v[130:133]
	v_mfma_f32_16x16x32_bf16 v[76:79], v[150:153], v[52:55], v[76:79]
	s_waitcnt lgkmcnt(1)
	v_mfma_f32_16x16x32_bf16 v[122:125], v[158:161], v[40:43], v[134:137]
	v_mfma_f32_16x16x32_bf16 v[130:133], v[158:161], v[52:55], v[80:83]
	s_waitcnt lgkmcnt(0)
	v_mfma_f32_16x16x32_bf16 v[134:137], v[188:191], v[40:43], v[32:35]
	v_mfma_f32_16x16x32_bf16 v[138:141], v[188:191], v[52:55], v[36:39]
	s_setprio 1
	s_nop 1
	ds_read_b128 v[36:39], v157 offset:35008
	ds_read_b128 v[52:55], v157 offset:39360
	ds_read_b128 v[80:83], v157 offset:43712
	ds_read_b128 v[142:145], v157 offset:48064
	ds_read_b128 v[146:149], v157 offset:52416
	ds_read_b128 v[150:153], v157 offset:56768
	ds_read_b128 v[158:161], v157 offset:61120
	ds_read_b128 v[188:191], v157 offset:65472
	s_setprio 2
	s_waitcnt lgkmcnt(7)
	v_mfma_f32_16x16x32_bf16 v[32:35], v[36:39], v[88:91], v[96:99]
	v_mfma_f32_16x16x32_bf16 v[36:39], v[36:39], v[92:95], v[44:47]
	s_waitcnt lgkmcnt(6)
	v_mfma_f32_16x16x32_bf16 v[40:43], v[52:55], v[88:91], v[56:59]
	v_mfma_f32_16x16x32_bf16 v[44:47], v[52:55], v[92:95], v[48:51]
	s_waitcnt lgkmcnt(5)
	v_mfma_f32_16x16x32_bf16 v[48:51], v[80:83], v[88:91], v[60:63]
	v_mfma_f32_16x16x32_bf16 v[52:55], v[80:83], v[92:95], v[64:67]
	s_waitcnt lgkmcnt(4)
	v_mfma_f32_16x16x32_bf16 v[56:59], v[142:145], v[88:91], v[84:87]
	v_mfma_f32_16x16x32_bf16 v[60:63], v[142:145], v[92:95], v[68:71]
	s_waitcnt lgkmcnt(3)
	v_mfma_f32_16x16x32_bf16 v[64:67], v[146:149], v[88:91], v[100:103]
	v_mfma_f32_16x16x32_bf16 v[68:71], v[146:149], v[92:95], v[72:75]
	s_waitcnt lgkmcnt(2)
	v_mfma_f32_16x16x32_bf16 v[72:75], v[150:153], v[88:91], v[118:121]
	v_mfma_f32_16x16x32_bf16 v[76:79], v[150:153], v[92:95], v[76:79]
	s_waitcnt lgkmcnt(1)
	v_mfma_f32_16x16x32_bf16 v[80:83], v[158:161], v[88:91], v[122:125]
	v_mfma_f32_16x16x32_bf16 v[84:87], v[158:161], v[92:95], v[130:133]
	s_waitcnt lgkmcnt(0)
	v_mfma_f32_16x16x32_bf16 v[88:91], v[188:191], v[88:91], v[134:137]
	v_mfma_f32_16x16x32_bf16 v[92:95], v[188:191], v[92:95], v[138:141]
	s_setprio 1
	s_lshl_b64 s[4:5], s[70:71], 15
	s_add_u32 s4, s80, s4
	s_addc_u32 s5, s81, s5
	v_lshlrev_b64 v[96:97], 8, v[104:105]
	v_lshl_add_u64 v[98:99], s[4:5], 0, v[96:97]
	s_lshl_b64 s[4:5], s[68:69], 15
	s_add_u32 s4, s80, s4
	s_addc_u32 s5, s81, s5
	v_lshl_add_u64 v[100:101], v[98:99], 0, v[128:129]
	v_lshl_add_u64 v[96:97], s[4:5], 0, v[96:97]
	s_barrier
	v_lshl_add_u64 v[102:103], v[96:97], 0, v[128:129]
	global_load_dwordx4 v[204:207], v[100:101], off
	s_movk_i32 s5, 0x2000
	v_add_co_u32_e32 v104, vcc, s5, v100
	s_movk_i32 s2, 0x4000
	s_nop 0
	v_addc_co_u32_e32 v105, vcc, 0, v101, vcc
	s_movk_i32 s4, 0x6000
	s_movk_i32 s6, 0x7000
	v_mov_b64_e32 v[132:133], v[10:11]
	v_mov_b64_e32 v[130:131], v[8:9]
	v_mov_b64_e32 v[136:137], v[6:7]
	v_mov_b64_e32 v[134:135], v[4:5]
	v_mov_b64_e32 v[140:141], v[2:3]
	v_mov_b64_e32 v[138:139], v[0:1]
	global_load_dwordx4 v[208:211], v[104:105], off offset:-4096
	global_load_dwordx4 v[216:219], v[104:105], off
	v_add_co_u32_e32 v104, vcc, s2, v100
	v_addc_co_u32_e32 v105, vcc, 0, v101, vcc
	global_load_dwordx4 v[220:223], v[104:105], off offset:-4096
	global_load_dwordx4 v[224:227], v[104:105], off
	v_add_co_u32_e32 v104, vcc, s4, v100
	v_addc_co_u32_e32 v105, vcc, 0, v101, vcc
	global_load_dwordx4 v[228:231], v[104:105], off offset:-4096
	global_load_dwordx4 v[232:235], v[104:105], off
	v_add_co_u32_e32 v96, vcc, s6, v100
	s_nop 1
	v_addc_co_u32_e32 v97, vcc, 0, v101, vcc
	global_load_dwordx4 v[236:239], v[96:97], off
	s_waitcnt vmcnt(0)
	ds_write_b128 v107, v[204:207]
	ds_write_b128 v107, v[208:211] offset:4352
	ds_write_b128 v107, v[216:219] offset:8704
	ds_write_b128 v107, v[220:223] offset:13056
	ds_write_b128 v107, v[224:227] offset:17408
	ds_write_b128 v107, v[228:231] offset:21760
	ds_write_b128 v107, v[232:235] offset:26112
	ds_write_b128 v107, v[236:239] offset:30464
	v_add_co_u32_e32 v100, vcc, s5, v102
	global_load_dwordx4 v[204:207], v[102:103], off
	v_addc_co_u32_e32 v101, vcc, 0, v103, vcc
	global_load_dwordx4 v[208:211], v[100:101], off offset:-4096
	global_load_dwordx4 v[216:219], v[100:101], off
	v_add_co_u32_e32 v100, vcc, s2, v102
	v_addc_co_u32_e32 v101, vcc, 0, v103, vcc
	global_load_dwordx4 v[220:223], v[100:101], off offset:-4096
	global_load_dwordx4 v[224:227], v[100:101], off
	v_add_co_u32_e32 v100, vcc, s4, v102
	v_addc_co_u32_e32 v101, vcc, 0, v103, vcc
	global_load_dwordx4 v[228:231], v[100:101], off offset:-4096
	global_load_dwordx4 v[232:235], v[100:101], off
	v_add_co_u32_e32 v96, vcc, s6, v102
	s_nop 1
	v_addc_co_u32_e32 v97, vcc, 0, v103, vcc
	global_load_dwordx4 v[236:239], v[96:97], off
	s_waitcnt vmcnt(0)
	ds_write_b128 v107, v[204:207] offset:34816
	ds_write_b128 v107, v[208:211] offset:39168
	ds_write_b128 v107, v[216:219] offset:43520
	ds_write_b128 v107, v[220:223] offset:47872
	ds_write_b128 v107, v[224:227] offset:52224
	ds_write_b128 v107, v[228:231] offset:56576
	ds_write_b128 v107, v[232:235] offset:60928
	ds_write_b128 v107, v[236:239] offset:65280
	v_mov_b64_e32 v[98:99], v[30:31]
	v_mov_b64_e32 v[96:97], v[28:29]
	s_waitcnt lgkmcnt(0)
	s_barrier
	s_nop 0
	v_lshlrev_b32_e32 v100, 16, v96
	v_and_b32_e32 v101, 0xffff0000, v96
	v_pk_mul_f32 v[100:101], v[116:117], v[100:101] op_sel_hi:[0,1]
	v_cvt_pk_bf16_f32 v96, v100, v101
	v_lshlrev_b32_e32 v100, 16, v97
	v_and_b32_e32 v101, 0xffff0000, v97
	v_pk_mul_f32 v[100:101], v[116:117], v[100:101] op_sel_hi:[0,1]
	v_cvt_pk_bf16_f32 v97, v100, v101
	v_lshlrev_b32_e32 v100, 16, v98
	v_and_b32_e32 v101, 0xffff0000, v98
	v_pk_mul_f32 v[100:101], v[116:117], v[100:101] op_sel_hi:[0,1]
	v_cvt_pk_bf16_f32 v98, v100, v101
	v_lshlrev_b32_e32 v100, 16, v99
	v_and_b32_e32 v101, 0xffff0000, v99
	v_pk_mul_f32 v[100:101], v[116:117], v[100:101] op_sel_hi:[0,1]
	v_cvt_pk_bf16_f32 v99, v100, v101
	v_mov_b64_e32 v[102:103], v[26:27]
	v_mov_b64_e32 v[100:101], v[24:25]
	s_nop 0
	v_lshlrev_b32_e32 v104, 16, v100
	v_and_b32_e32 v105, 0xffff0000, v100
	v_pk_mul_f32 v[104:105], v[114:115], v[104:105] op_sel_hi:[0,1]
	v_cvt_pk_bf16_f32 v100, v104, v105
	v_lshlrev_b32_e32 v104, 16, v101
	v_and_b32_e32 v105, 0xffff0000, v101
	v_pk_mul_f32 v[104:105], v[114:115], v[104:105] op_sel_hi:[0,1]
	v_cvt_pk_bf16_f32 v101, v104, v105
	v_lshlrev_b32_e32 v104, 16, v102
	v_and_b32_e32 v105, 0xffff0000, v102
	v_pk_mul_f32 v[104:105], v[114:115], v[104:105] op_sel_hi:[0,1]
	v_cvt_pk_bf16_f32 v102, v104, v105
	v_lshlrev_b32_e32 v104, 16, v103
	v_and_b32_e32 v105, 0xffff0000, v103
	v_pk_mul_f32 v[104:105], v[114:115], v[104:105] op_sel_hi:[0,1]
	v_cvt_pk_bf16_f32 v103, v104, v105
	v_mov_b64_e32 v[106:107], v[22:23]
	v_mov_b64_e32 v[104:105], v[20:21]
	s_nop 0
	v_lshlrev_b32_e32 v118, 16, v104
	v_and_b32_e32 v119, 0xffff0000, v104
	v_pk_mul_f32 v[118:119], v[116:117], v[118:119] op_sel_hi:[0,1]
	v_cvt_pk_bf16_f32 v104, v118, v119
	v_lshlrev_b32_e32 v118, 16, v105
	v_and_b32_e32 v119, 0xffff0000, v105
	v_pk_mul_f32 v[118:119], v[116:117], v[118:119] op_sel_hi:[0,1]
	v_cvt_pk_bf16_f32 v105, v118, v119
	v_lshlrev_b32_e32 v118, 16, v106
	v_and_b32_e32 v119, 0xffff0000, v106
	v_pk_mul_f32 v[118:119], v[116:117], v[118:119] op_sel_hi:[0,1]
	v_cvt_pk_bf16_f32 v106, v118, v119
	v_lshlrev_b32_e32 v118, 16, v107
	v_and_b32_e32 v119, 0xffff0000, v107
	v_pk_mul_f32 v[118:119], v[116:117], v[118:119] op_sel_hi:[0,1]
	v_cvt_pk_bf16_f32 v107, v118, v119
	v_mov_b64_e32 v[120:121], v[18:19]
	v_mov_b64_e32 v[118:119], v[16:17]
	s_nop 0
	v_lshlrev_b32_e32 v122, 16, v118
	v_and_b32_e32 v123, 0xffff0000, v118
	v_pk_mul_f32 v[122:123], v[114:115], v[122:123] op_sel_hi:[0,1]
	v_cvt_pk_bf16_f32 v118, v122, v123
	v_lshlrev_b32_e32 v122, 16, v119
	v_and_b32_e32 v123, 0xffff0000, v119
	v_pk_mul_f32 v[122:123], v[114:115], v[122:123] op_sel_hi:[0,1]
	v_cvt_pk_bf16_f32 v119, v122, v123
	v_lshlrev_b32_e32 v122, 16, v120
	v_and_b32_e32 v123, 0xffff0000, v120
	v_pk_mul_f32 v[122:123], v[114:115], v[122:123] op_sel_hi:[0,1]
	v_cvt_pk_bf16_f32 v120, v122, v123
	v_lshlrev_b32_e32 v122, 16, v121
	v_and_b32_e32 v123, 0xffff0000, v121
	v_pk_mul_f32 v[122:123], v[114:115], v[122:123] op_sel_hi:[0,1]
	v_cvt_pk_bf16_f32 v121, v122, v123
	v_mov_b64_e32 v[124:125], v[14:15]
	v_mov_b64_e32 v[122:123], v[12:13]
	s_nop 0
	v_lshlrev_b32_e32 v126, 16, v122
	v_and_b32_e32 v127, 0xffff0000, v122
	v_pk_mul_f32 v[126:127], v[116:117], v[126:127] op_sel_hi:[0,1]
	v_cvt_pk_bf16_f32 v122, v126, v127
	v_lshlrev_b32_e32 v126, 16, v123
	v_and_b32_e32 v127, 0xffff0000, v123
	v_pk_mul_f32 v[126:127], v[116:117], v[126:127] op_sel_hi:[0,1]
	v_cvt_pk_bf16_f32 v123, v126, v127
	v_lshlrev_b32_e32 v126, 16, v124
	v_and_b32_e32 v127, 0xffff0000, v124
	v_pk_mul_f32 v[126:127], v[116:117], v[126:127] op_sel_hi:[0,1]
	v_cvt_pk_bf16_f32 v124, v126, v127
	v_lshlrev_b32_e32 v126, 16, v125
	v_and_b32_e32 v127, 0xffff0000, v125
	v_pk_mul_f32 v[126:127], v[116:117], v[126:127] op_sel_hi:[0,1]
	v_cvt_pk_bf16_f32 v125, v126, v127
	v_lshlrev_b32_e32 v126, 16, v130
	v_and_b32_e32 v127, 0xffff0000, v130
	v_pk_mul_f32 v[126:127], v[114:115], v[126:127] op_sel_hi:[0,1]
	v_cvt_pk_bf16_f32 v130, v126, v127
	v_lshlrev_b32_e32 v126, 16, v131
	v_and_b32_e32 v127, 0xffff0000, v131
	v_pk_mul_f32 v[126:127], v[114:115], v[126:127] op_sel_hi:[0,1]
	v_cvt_pk_bf16_f32 v131, v126, v127
	v_lshlrev_b32_e32 v126, 16, v132
	v_and_b32_e32 v127, 0xffff0000, v132
	v_pk_mul_f32 v[126:127], v[114:115], v[126:127] op_sel_hi:[0,1]
	v_cvt_pk_bf16_f32 v132, v126, v127
	v_lshlrev_b32_e32 v126, 16, v133
	v_and_b32_e32 v127, 0xffff0000, v133
	v_pk_mul_f32 v[126:127], v[114:115], v[126:127] op_sel_hi:[0,1]
	v_cvt_pk_bf16_f32 v133, v126, v127
	v_lshlrev_b32_e32 v126, 16, v134
	v_and_b32_e32 v127, 0xffff0000, v134
	v_pk_mul_f32 v[126:127], v[116:117], v[126:127] op_sel_hi:[0,1]
	v_cvt_pk_bf16_f32 v134, v126, v127
	v_lshlrev_b32_e32 v126, 16, v135
	v_and_b32_e32 v127, 0xffff0000, v135
	v_pk_mul_f32 v[126:127], v[116:117], v[126:127] op_sel_hi:[0,1]
	v_cvt_pk_bf16_f32 v135, v126, v127
	v_lshlrev_b32_e32 v126, 16, v136
	v_and_b32_e32 v127, 0xffff0000, v136
	v_pk_mul_f32 v[126:127], v[116:117], v[126:127] op_sel_hi:[0,1]
	v_cvt_pk_bf16_f32 v136, v126, v127
	v_lshlrev_b32_e32 v126, 16, v137
	v_and_b32_e32 v127, 0xffff0000, v137
	v_pk_mul_f32 v[116:117], v[116:117], v[126:127] op_sel_hi:[0,1]
	v_cvt_pk_bf16_f32 v137, v116, v117
	v_lshlrev_b32_e32 v116, 16, v138
	v_and_b32_e32 v117, 0xffff0000, v138
	v_pk_mul_f32 v[116:117], v[114:115], v[116:117] op_sel_hi:[0,1]
	v_cvt_pk_bf16_f32 v138, v116, v117
	v_lshlrev_b32_e32 v116, 16, v139
	v_and_b32_e32 v117, 0xffff0000, v139
	v_pk_mul_f32 v[116:117], v[114:115], v[116:117] op_sel_hi:[0,1]
	v_cvt_pk_bf16_f32 v139, v116, v117
	v_lshlrev_b32_e32 v116, 16, v140
	v_and_b32_e32 v117, 0xffff0000, v140
	v_pk_mul_f32 v[116:117], v[114:115], v[116:117] op_sel_hi:[0,1]
	v_cvt_pk_bf16_f32 v140, v116, v117
	v_lshlrev_b32_e32 v116, 16, v141
	v_and_b32_e32 v117, 0xffff0000, v141
	v_pk_mul_f32 v[114:115], v[114:115], v[116:117] op_sel_hi:[0,1]
	v_cvt_pk_bf16_f32 v141, v114, v115
	ds_read_b128 v[114:117], v157
	ds_read_b128 v[142:145], v157 offset:4352
	ds_read_b128 v[146:149], v157 offset:8704
	ds_read_b128 v[150:153], v157 offset:13056
	ds_read_b128 v[158:161], v157 offset:17408
	ds_read_b128 v[188:191], v157 offset:21760
	ds_read_b128 v[192:195], v157 offset:26112
	ds_read_b128 v[196:199], v157 offset:30464
	s_setprio 2
	s_waitcnt lgkmcnt(7)
	v_mfma_f32_16x16x32_bf16 v[32:35], v[114:117], v[96:99], v[32:35]
	v_mfma_f32_16x16x32_bf16 v[36:39], v[114:117], v[100:103], v[36:39]
	s_waitcnt lgkmcnt(6)
	v_mfma_f32_16x16x32_bf16 v[40:43], v[142:145], v[96:99], v[40:43]
	v_mfma_f32_16x16x32_bf16 v[44:47], v[142:145], v[100:103], v[44:47]
	s_waitcnt lgkmcnt(5)
	v_mfma_f32_16x16x32_bf16 v[48:51], v[146:149], v[96:99], v[48:51]
	v_mfma_f32_16x16x32_bf16 v[52:55], v[146:149], v[100:103], v[52:55]
	s_waitcnt lgkmcnt(4)
	v_mfma_f32_16x16x32_bf16 v[56:59], v[150:153], v[96:99], v[56:59]
	v_mfma_f32_16x16x32_bf16 v[60:63], v[150:153], v[100:103], v[60:63]
	s_waitcnt lgkmcnt(3)
	v_mfma_f32_16x16x32_bf16 v[64:67], v[158:161], v[96:99], v[64:67]
	v_mfma_f32_16x16x32_bf16 v[68:71], v[158:161], v[100:103], v[68:71]
	s_waitcnt lgkmcnt(2)
	v_mfma_f32_16x16x32_bf16 v[72:75], v[188:191], v[96:99], v[72:75]
	v_mfma_f32_16x16x32_bf16 v[76:79], v[188:191], v[100:103], v[76:79]
	s_waitcnt lgkmcnt(1)
	v_mfma_f32_16x16x32_bf16 v[80:83], v[192:195], v[96:99], v[80:83]
	v_mfma_f32_16x16x32_bf16 v[84:87], v[192:195], v[100:103], v[84:87]
	s_waitcnt lgkmcnt(0)
	v_mfma_f32_16x16x32_bf16 v[88:91], v[196:199], v[96:99], v[88:91]
	v_mfma_f32_16x16x32_bf16 v[92:95], v[196:199], v[100:103], v[92:95]
	s_setprio 1
	ds_read_b128 v[96:99], v157 offset:64
	ds_read_b128 v[100:103], v157 offset:4416
	ds_read_b128 v[114:117], v157 offset:8768
	ds_read_b128 v[142:145], v157 offset:13120
	ds_read_b128 v[146:149], v157 offset:17472
	ds_read_b128 v[150:153], v157 offset:21824
	ds_read_b128 v[158:161], v157 offset:26176
	ds_read_b128 v[188:191], v157 offset:30528
	s_setprio 2
	s_waitcnt lgkmcnt(7)
	v_mfma_f32_16x16x32_bf16 v[32:35], v[96:99], v[104:107], v[32:35]
	v_mfma_f32_16x16x32_bf16 v[36:39], v[96:99], v[118:121], v[36:39]
	s_waitcnt lgkmcnt(6)
	v_mfma_f32_16x16x32_bf16 v[40:43], v[100:103], v[104:107], v[40:43]
	v_mfma_f32_16x16x32_bf16 v[44:47], v[100:103], v[118:121], v[44:47]
	s_waitcnt lgkmcnt(5)
	v_mfma_f32_16x16x32_bf16 v[48:51], v[114:117], v[104:107], v[48:51]
	v_mfma_f32_16x16x32_bf16 v[52:55], v[114:117], v[118:121], v[52:55]
	s_waitcnt lgkmcnt(4)
	v_mfma_f32_16x16x32_bf16 v[56:59], v[142:145], v[104:107], v[56:59]
	v_mfma_f32_16x16x32_bf16 v[60:63], v[142:145], v[118:121], v[60:63]
	s_waitcnt lgkmcnt(3)
	v_mfma_f32_16x16x32_bf16 v[64:67], v[146:149], v[104:107], v[64:67]
	v_mfma_f32_16x16x32_bf16 v[68:71], v[146:149], v[118:121], v[68:71]
	s_waitcnt lgkmcnt(2)
	v_mfma_f32_16x16x32_bf16 v[72:75], v[150:153], v[104:107], v[72:75]
	v_mfma_f32_16x16x32_bf16 v[76:79], v[150:153], v[118:121], v[76:79]
	s_waitcnt lgkmcnt(1)
	v_mfma_f32_16x16x32_bf16 v[80:83], v[158:161], v[104:107], v[80:83]
	v_mfma_f32_16x16x32_bf16 v[84:87], v[158:161], v[118:121], v[84:87]
	s_waitcnt lgkmcnt(0)
	v_mfma_f32_16x16x32_bf16 v[88:91], v[188:191], v[104:107], v[88:91]
	v_mfma_f32_16x16x32_bf16 v[92:95], v[188:191], v[118:121], v[92:95]
	s_setprio 1
	ds_read_b128 v[96:99], v157 offset:128
	ds_read_b128 v[100:103], v157 offset:4480
	ds_read_b128 v[104:107], v157 offset:8832
	ds_read_b128 v[114:117], v157 offset:13184
	ds_read_b128 v[118:121], v157 offset:17536
	ds_read_b128 v[142:145], v157 offset:21888
	ds_read_b128 v[146:149], v157 offset:26240
	ds_read_b128 v[150:153], v157 offset:30592
	s_setprio 2
	s_waitcnt lgkmcnt(7)
	v_mfma_f32_16x16x32_bf16 v[32:35], v[96:99], v[122:125], v[32:35]
	v_mfma_f32_16x16x32_bf16 v[36:39], v[96:99], v[130:133], v[36:39]
	s_waitcnt lgkmcnt(6)
	v_mfma_f32_16x16x32_bf16 v[40:43], v[100:103], v[122:125], v[40:43]
	v_mfma_f32_16x16x32_bf16 v[44:47], v[100:103], v[130:133], v[44:47]
	s_waitcnt lgkmcnt(5)
	v_mfma_f32_16x16x32_bf16 v[48:51], v[104:107], v[122:125], v[48:51]
	v_mfma_f32_16x16x32_bf16 v[52:55], v[104:107], v[130:133], v[52:55]
	s_waitcnt lgkmcnt(4)
	v_mfma_f32_16x16x32_bf16 v[56:59], v[114:117], v[122:125], v[56:59]
	v_mfma_f32_16x16x32_bf16 v[60:63], v[114:117], v[130:133], v[60:63]
	s_waitcnt lgkmcnt(3)
	v_mfma_f32_16x16x32_bf16 v[64:67], v[118:121], v[122:125], v[64:67]
	v_mfma_f32_16x16x32_bf16 v[68:71], v[118:121], v[130:133], v[68:71]
	s_waitcnt lgkmcnt(2)
	v_mfma_f32_16x16x32_bf16 v[72:75], v[142:145], v[122:125], v[72:75]
	v_mfma_f32_16x16x32_bf16 v[76:79], v[142:145], v[130:133], v[76:79]
	s_waitcnt lgkmcnt(1)
	v_mfma_f32_16x16x32_bf16 v[80:83], v[146:149], v[122:125], v[80:83]
	v_mfma_f32_16x16x32_bf16 v[84:87], v[146:149], v[130:133], v[84:87]
	s_waitcnt lgkmcnt(0)
	v_mfma_f32_16x16x32_bf16 v[88:91], v[150:153], v[122:125], v[88:91]
	v_mfma_f32_16x16x32_bf16 v[92:95], v[150:153], v[130:133], v[92:95]
	s_setprio 1
	ds_read_b128 v[96:99], v157 offset:192
	ds_read_b128 v[100:103], v157 offset:4544
	ds_read_b128 v[104:107], v157 offset:8896
	ds_read_b128 v[114:117], v157 offset:13248
	ds_read_b128 v[118:121], v157 offset:17600
	ds_read_b128 v[122:125], v157 offset:21952
	ds_read_b128 v[130:133], v157 offset:26304
	ds_read_b128 v[142:145], v157 offset:30656
	s_setprio 2
	s_waitcnt lgkmcnt(7)
	v_mfma_f32_16x16x32_bf16 v[32:35], v[96:99], v[134:137], v[32:35]
	v_mfma_f32_16x16x32_bf16 v[36:39], v[96:99], v[138:141], v[36:39]
	s_waitcnt lgkmcnt(6)
	v_mfma_f32_16x16x32_bf16 v[40:43], v[100:103], v[134:137], v[40:43]
	v_mfma_f32_16x16x32_bf16 v[44:47], v[100:103], v[138:141], v[44:47]
	s_waitcnt lgkmcnt(5)
	v_mfma_f32_16x16x32_bf16 v[48:51], v[104:107], v[134:137], v[48:51]
	v_mfma_f32_16x16x32_bf16 v[52:55], v[104:107], v[138:141], v[52:55]
	s_waitcnt lgkmcnt(4)
	v_mfma_f32_16x16x32_bf16 v[56:59], v[114:117], v[134:137], v[56:59]
	v_mfma_f32_16x16x32_bf16 v[60:63], v[114:117], v[138:141], v[60:63]
	s_waitcnt lgkmcnt(3)
	v_mfma_f32_16x16x32_bf16 v[64:67], v[118:121], v[134:137], v[64:67]
	v_mfma_f32_16x16x32_bf16 v[68:71], v[118:121], v[138:141], v[68:71]
	s_waitcnt lgkmcnt(2)
	v_mfma_f32_16x16x32_bf16 v[72:75], v[122:125], v[134:137], v[72:75]
	v_mfma_f32_16x16x32_bf16 v[76:79], v[122:125], v[138:141], v[76:79]
	s_waitcnt lgkmcnt(1)
	v_mfma_f32_16x16x32_bf16 v[80:83], v[130:133], v[134:137], v[80:83]
	v_mfma_f32_16x16x32_bf16 v[84:87], v[130:133], v[138:141], v[84:87]
	s_waitcnt lgkmcnt(0)
	v_mfma_f32_16x16x32_bf16 v[88:91], v[142:145], v[134:137], v[88:91]
	v_mfma_f32_16x16x32_bf16 v[92:95], v[142:145], v[138:141], v[92:95]
	s_setprio 1
	s_nop 0
	v_lshlrev_b32_e32 v96, 16, v28
	v_and_b32_e32 v97, 0xffff0000, v28
	v_pk_mul_f32 v[96:97], v[112:113], v[96:97] op_sel_hi:[0,1]
	v_cvt_pk_bf16_f32 v28, v96, v97
	v_lshlrev_b32_e32 v96, 16, v29
	v_and_b32_e32 v97, 0xffff0000, v29
	v_pk_mul_f32 v[96:97], v[112:113], v[96:97] op_sel_hi:[0,1]
	v_cvt_pk_bf16_f32 v29, v96, v97
	v_lshlrev_b32_e32 v96, 16, v30
	v_and_b32_e32 v97, 0xffff0000, v30
	v_pk_mul_f32 v[96:97], v[112:113], v[96:97] op_sel_hi:[0,1]
	v_cvt_pk_bf16_f32 v30, v96, v97
	v_lshlrev_b32_e32 v96, 16, v31
	v_and_b32_e32 v97, 0xffff0000, v31
	v_pk_mul_f32 v[96:97], v[112:113], v[96:97] op_sel_hi:[0,1]
	v_cvt_pk_bf16_f32 v31, v96, v97
	v_lshlrev_b32_e32 v96, 16, v24
	v_and_b32_e32 v97, 0xffff0000, v24
	v_pk_mul_f32 v[96:97], v[110:111], v[96:97] op_sel_hi:[0,1]
	v_cvt_pk_bf16_f32 v24, v96, v97
	v_lshlrev_b32_e32 v96, 16, v25
	v_and_b32_e32 v97, 0xffff0000, v25
	v_pk_mul_f32 v[96:97], v[110:111], v[96:97] op_sel_hi:[0,1]
	v_cvt_pk_bf16_f32 v25, v96, v97
	v_lshlrev_b32_e32 v96, 16, v26
	v_and_b32_e32 v97, 0xffff0000, v26
	v_pk_mul_f32 v[96:97], v[110:111], v[96:97] op_sel_hi:[0,1]
	v_cvt_pk_bf16_f32 v26, v96, v97
	v_lshlrev_b32_e32 v96, 16, v27
	v_and_b32_e32 v97, 0xffff0000, v27
	v_pk_mul_f32 v[96:97], v[110:111], v[96:97] op_sel_hi:[0,1]
	v_cvt_pk_bf16_f32 v27, v96, v97
	v_lshlrev_b32_e32 v96, 16, v20
	v_and_b32_e32 v97, 0xffff0000, v20
	v_pk_mul_f32 v[96:97], v[112:113], v[96:97] op_sel_hi:[0,1]
	v_cvt_pk_bf16_f32 v20, v96, v97
	v_lshlrev_b32_e32 v96, 16, v21
	v_and_b32_e32 v97, 0xffff0000, v21
	v_pk_mul_f32 v[96:97], v[112:113], v[96:97] op_sel_hi:[0,1]
	v_cvt_pk_bf16_f32 v21, v96, v97
	v_lshlrev_b32_e32 v96, 16, v22
	v_and_b32_e32 v97, 0xffff0000, v22
	v_pk_mul_f32 v[96:97], v[112:113], v[96:97] op_sel_hi:[0,1]
	v_cvt_pk_bf16_f32 v22, v96, v97
	v_lshlrev_b32_e32 v96, 16, v23
	v_and_b32_e32 v97, 0xffff0000, v23
	v_pk_mul_f32 v[96:97], v[112:113], v[96:97] op_sel_hi:[0,1]
	v_cvt_pk_bf16_f32 v23, v96, v97
	v_lshlrev_b32_e32 v96, 16, v16
	v_and_b32_e32 v97, 0xffff0000, v16
	v_pk_mul_f32 v[96:97], v[110:111], v[96:97] op_sel_hi:[0,1]
	v_cvt_pk_bf16_f32 v16, v96, v97
	v_lshlrev_b32_e32 v96, 16, v17
	v_and_b32_e32 v97, 0xffff0000, v17
	v_pk_mul_f32 v[96:97], v[110:111], v[96:97] op_sel_hi:[0,1]
	v_cvt_pk_bf16_f32 v17, v96, v97
	v_lshlrev_b32_e32 v96, 16, v18
	v_and_b32_e32 v97, 0xffff0000, v18
	v_pk_mul_f32 v[96:97], v[110:111], v[96:97] op_sel_hi:[0,1]
	v_cvt_pk_bf16_f32 v18, v96, v97
	v_lshlrev_b32_e32 v96, 16, v19
	v_and_b32_e32 v97, 0xffff0000, v19
	v_pk_mul_f32 v[96:97], v[110:111], v[96:97] op_sel_hi:[0,1]
	v_cvt_pk_bf16_f32 v19, v96, v97
	v_lshlrev_b32_e32 v96, 16, v12
	v_and_b32_e32 v97, 0xffff0000, v12
	v_pk_mul_f32 v[96:97], v[112:113], v[96:97] op_sel_hi:[0,1]
	v_cvt_pk_bf16_f32 v12, v96, v97
	v_lshlrev_b32_e32 v96, 16, v13
	v_and_b32_e32 v97, 0xffff0000, v13
	v_pk_mul_f32 v[96:97], v[112:113], v[96:97] op_sel_hi:[0,1]
	v_cvt_pk_bf16_f32 v13, v96, v97
	v_lshlrev_b32_e32 v96, 16, v14
	v_and_b32_e32 v97, 0xffff0000, v14
	v_pk_mul_f32 v[96:97], v[112:113], v[96:97] op_sel_hi:[0,1]
	v_cvt_pk_bf16_f32 v14, v96, v97
	v_lshlrev_b32_e32 v96, 16, v15
	v_and_b32_e32 v97, 0xffff0000, v15
	v_pk_mul_f32 v[96:97], v[112:113], v[96:97] op_sel_hi:[0,1]
	v_cvt_pk_bf16_f32 v15, v96, v97
	v_lshlrev_b32_e32 v96, 16, v8
	v_and_b32_e32 v97, 0xffff0000, v8
	v_pk_mul_f32 v[96:97], v[110:111], v[96:97] op_sel_hi:[0,1]
	v_cvt_pk_bf16_f32 v8, v96, v97
	v_lshlrev_b32_e32 v96, 16, v9
	v_and_b32_e32 v97, 0xffff0000, v9
	v_pk_mul_f32 v[96:97], v[110:111], v[96:97] op_sel_hi:[0,1]
	v_cvt_pk_bf16_f32 v9, v96, v97
	v_lshlrev_b32_e32 v96, 16, v10
	v_and_b32_e32 v97, 0xffff0000, v10
	v_pk_mul_f32 v[96:97], v[110:111], v[96:97] op_sel_hi:[0,1]
	v_cvt_pk_bf16_f32 v10, v96, v97
	v_lshlrev_b32_e32 v96, 16, v11
	v_and_b32_e32 v97, 0xffff0000, v11
	v_pk_mul_f32 v[96:97], v[110:111], v[96:97] op_sel_hi:[0,1]
	v_cvt_pk_bf16_f32 v11, v96, v97
	v_lshlrev_b32_e32 v96, 16, v4
	v_and_b32_e32 v97, 0xffff0000, v4
	v_lshlrev_b32_e32 v4, 16, v5
	v_and_b32_e32 v5, 0xffff0000, v5
	v_pk_mul_f32 v[96:97], v[112:113], v[96:97] op_sel_hi:[0,1]
	v_pk_mul_f32 v[4:5], v[112:113], v[4:5] op_sel_hi:[0,1]
	v_cvt_pk_bf16_f32 v96, v96, v97
	v_cvt_pk_bf16_f32 v97, v4, v5
	v_lshlrev_b32_e32 v4, 16, v6
	v_and_b32_e32 v5, 0xffff0000, v6
	v_pk_mul_f32 v[4:5], v[112:113], v[4:5] op_sel_hi:[0,1]
	v_cvt_pk_bf16_f32 v98, v4, v5
	v_lshlrev_b32_e32 v4, 16, v7
	v_and_b32_e32 v5, 0xffff0000, v7
	v_pk_mul_f32 v[4:5], v[112:113], v[4:5] op_sel_hi:[0,1]
	v_cvt_pk_bf16_f32 v99, v4, v5
	s_nop 0
	v_lshlrev_b32_e32 v4, 16, v0
	v_and_b32_e32 v5, 0xffff0000, v0
	v_pk_mul_f32 v[4:5], v[110:111], v[4:5] op_sel_hi:[0,1]
	v_cvt_pk_bf16_f32 v0, v4, v5
	v_lshlrev_b32_e32 v4, 16, v1
	v_and_b32_e32 v5, 0xffff0000, v1
	v_pk_mul_f32 v[4:5], v[110:111], v[4:5] op_sel_hi:[0,1]
	v_cvt_pk_bf16_f32 v1, v4, v5
	v_lshlrev_b32_e32 v4, 16, v2
	v_and_b32_e32 v5, 0xffff0000, v2
	v_pk_mul_f32 v[4:5], v[110:111], v[4:5] op_sel_hi:[0,1]
	v_cvt_pk_bf16_f32 v2, v4, v5
	v_lshlrev_b32_e32 v4, 16, v3
	v_and_b32_e32 v5, 0xffff0000, v3
	v_pk_mul_f32 v[4:5], v[110:111], v[4:5] op_sel_hi:[0,1]
	v_cvt_pk_bf16_f32 v3, v4, v5
	ds_read_b128 v[4:7], v157 offset:34816
	ds_read_b128 v[100:103], v157 offset:39168
	ds_read_b128 v[104:107], v157 offset:43520
	ds_read_b128 v[110:113], v157 offset:47872
	ds_read_b128 v[114:117], v157 offset:52224
	ds_read_b128 v[118:121], v157 offset:56576
	ds_read_b128 v[122:125], v157 offset:60928
	ds_read_b128 v[130:133], v157 offset:65280
	s_setprio 2
	s_waitcnt lgkmcnt(7)
	v_mfma_f32_16x16x32_bf16 v[32:35], v[4:7], v[28:31], v[32:35]
	v_mfma_f32_16x16x32_bf16 v[4:7], v[4:7], v[24:27], v[36:39]
	s_waitcnt lgkmcnt(6)
	v_mfma_f32_16x16x32_bf16 v[36:39], v[100:103], v[28:31], v[40:43]
	v_mfma_f32_16x16x32_bf16 v[40:43], v[100:103], v[24:27], v[44:47]
	s_waitcnt lgkmcnt(5)
	v_mfma_f32_16x16x32_bf16 v[44:47], v[104:107], v[28:31], v[48:51]
	v_mfma_f32_16x16x32_bf16 v[48:51], v[104:107], v[24:27], v[52:55]
	s_waitcnt lgkmcnt(4)
	v_mfma_f32_16x16x32_bf16 v[52:55], v[110:113], v[28:31], v[56:59]
	v_mfma_f32_16x16x32_bf16 v[56:59], v[110:113], v[24:27], v[60:63]
	s_waitcnt lgkmcnt(3)
	v_mfma_f32_16x16x32_bf16 v[60:63], v[114:117], v[28:31], v[64:67]
	v_mfma_f32_16x16x32_bf16 v[64:67], v[114:117], v[24:27], v[68:71]
	s_waitcnt lgkmcnt(2)
	v_mfma_f32_16x16x32_bf16 v[68:71], v[118:121], v[28:31], v[72:75]
	v_mfma_f32_16x16x32_bf16 v[72:75], v[118:121], v[24:27], v[76:79]
	s_waitcnt lgkmcnt(1)
	v_mfma_f32_16x16x32_bf16 v[76:79], v[122:125], v[28:31], v[80:83]
	v_mfma_f32_16x16x32_bf16 v[80:83], v[122:125], v[24:27], v[84:87]
	s_waitcnt lgkmcnt(0)
	v_mfma_f32_16x16x32_bf16 v[28:31], v[130:133], v[28:31], v[88:91]
	v_mfma_f32_16x16x32_bf16 v[24:27], v[130:133], v[24:27], v[92:95]
	s_setprio 1
	ds_read_b128 v[84:87], v157 offset:34880
	ds_read_b128 v[88:91], v157 offset:39232
	ds_read_b128 v[92:95], v157 offset:43584
	ds_read_b128 v[100:103], v157 offset:47936
	ds_read_b128 v[104:107], v157 offset:52288
	ds_read_b128 v[110:113], v157 offset:56640
	ds_read_b128 v[114:117], v157 offset:60992
	ds_read_b128 v[118:121], v157 offset:65344
	s_setprio 2
	s_waitcnt lgkmcnt(7)
	v_mfma_f32_16x16x32_bf16 v[32:35], v[84:87], v[20:23], v[32:35]
	v_mfma_f32_16x16x32_bf16 v[4:7], v[84:87], v[16:19], v[4:7]
	s_waitcnt lgkmcnt(6)
	v_mfma_f32_16x16x32_bf16 v[36:39], v[88:91], v[20:23], v[36:39]
	v_mfma_f32_16x16x32_bf16 v[40:43], v[88:91], v[16:19], v[40:43]
	s_waitcnt lgkmcnt(5)
	v_mfma_f32_16x16x32_bf16 v[44:47], v[92:95], v[20:23], v[44:47]
	v_mfma_f32_16x16x32_bf16 v[48:51], v[92:95], v[16:19], v[48:51]
	s_waitcnt lgkmcnt(4)
	v_mfma_f32_16x16x32_bf16 v[52:55], v[100:103], v[20:23], v[52:55]
	v_mfma_f32_16x16x32_bf16 v[56:59], v[100:103], v[16:19], v[56:59]
	s_waitcnt lgkmcnt(3)
	v_mfma_f32_16x16x32_bf16 v[60:63], v[104:107], v[20:23], v[60:63]
	v_mfma_f32_16x16x32_bf16 v[64:67], v[104:107], v[16:19], v[64:67]
	s_waitcnt lgkmcnt(2)
	v_mfma_f32_16x16x32_bf16 v[68:71], v[110:113], v[20:23], v[68:71]
	v_mfma_f32_16x16x32_bf16 v[72:75], v[110:113], v[16:19], v[72:75]
	s_waitcnt lgkmcnt(1)
	v_mfma_f32_16x16x32_bf16 v[76:79], v[114:117], v[20:23], v[76:79]
	v_mfma_f32_16x16x32_bf16 v[80:83], v[114:117], v[16:19], v[80:83]
	s_waitcnt lgkmcnt(0)
	v_mfma_f32_16x16x32_bf16 v[20:23], v[118:121], v[20:23], v[28:31]
	v_mfma_f32_16x16x32_bf16 v[16:19], v[118:121], v[16:19], v[24:27]
	s_setprio 1
	s_nop 1
	ds_read_b128 v[24:27], v157 offset:34944
	ds_read_b128 v[28:31], v157 offset:39296
	ds_read_b128 v[84:87], v157 offset:43648
	ds_read_b128 v[88:91], v157 offset:48000
	ds_read_b128 v[92:95], v157 offset:52352
	ds_read_b128 v[100:103], v157 offset:56704
	ds_read_b128 v[104:107], v157 offset:61056
	ds_read_b128 v[110:113], v157 offset:65408
	s_setprio 2
	s_waitcnt lgkmcnt(7)
	v_mfma_f32_16x16x32_bf16 v[32:35], v[24:27], v[12:15], v[32:35]
	v_mfma_f32_16x16x32_bf16 v[4:7], v[24:27], v[8:11], v[4:7]
	s_waitcnt lgkmcnt(6)
	v_mfma_f32_16x16x32_bf16 v[24:27], v[28:31], v[12:15], v[36:39]
	v_mfma_f32_16x16x32_bf16 v[36:39], v[28:31], v[8:11], v[40:43]
	s_waitcnt lgkmcnt(5)
	v_mfma_f32_16x16x32_bf16 v[40:43], v[84:87], v[12:15], v[44:47]
	v_mfma_f32_16x16x32_bf16 v[44:47], v[84:87], v[8:11], v[48:51]
	s_waitcnt lgkmcnt(4)
	v_mfma_f32_16x16x32_bf16 v[48:51], v[88:91], v[12:15], v[52:55]
	v_mfma_f32_16x16x32_bf16 v[84:87], v[88:91], v[8:11], v[56:59]
	s_waitcnt lgkmcnt(3)
	v_mfma_f32_16x16x32_bf16 v[88:91], v[92:95], v[12:15], v[60:63]
	v_mfma_f32_16x16x32_bf16 v[64:67], v[92:95], v[8:11], v[64:67]
	s_waitcnt lgkmcnt(2)
	v_mfma_f32_16x16x32_bf16 v[68:71], v[100:103], v[12:15], v[68:71]
	v_mfma_f32_16x16x32_bf16 v[72:75], v[100:103], v[8:11], v[72:75]
	s_waitcnt lgkmcnt(1)
	v_mfma_f32_16x16x32_bf16 v[76:79], v[104:107], v[12:15], v[76:79]
	v_mfma_f32_16x16x32_bf16 v[80:83], v[104:107], v[8:11], v[80:83]
	s_waitcnt lgkmcnt(0)
	v_mfma_f32_16x16x32_bf16 v[92:95], v[110:113], v[12:15], v[20:23]
	v_mfma_f32_16x16x32_bf16 v[100:103], v[110:113], v[8:11], v[16:19]
	s_setprio 1
	ds_read_b128 v[8:11], v157 offset:35008
	ds_read_b128 v[12:15], v157 offset:39360
	ds_read_b128 v[16:19], v157 offset:43712
	ds_read_b128 v[104:107], v157 offset:48064
	ds_read_b128 v[110:113], v157 offset:52416
	ds_read_b128 v[114:117], v157 offset:56768
	ds_read_b128 v[118:121], v157 offset:61120
	ds_read_b128 v[122:125], v157 offset:65472
	s_setprio 2
	s_waitcnt lgkmcnt(7)
	v_mfma_f32_16x16x32_bf16 v[60:63], v[8:11], v[96:99], v[32:35]
	v_mfma_f32_16x16x32_bf16 v[28:31], v[8:11], v[0:3], v[4:7]
	s_waitcnt lgkmcnt(6)
	v_mfma_f32_16x16x32_bf16 v[56:59], v[12:15], v[96:99], v[24:27]
	v_mfma_f32_16x16x32_bf16 v[24:27], v[12:15], v[0:3], v[36:39]
	s_waitcnt lgkmcnt(5)
	v_mfma_f32_16x16x32_bf16 v[52:55], v[16:19], v[96:99], v[40:43]
	v_mfma_f32_16x16x32_bf16 v[20:23], v[16:19], v[0:3], v[44:47]
	s_waitcnt lgkmcnt(4)
	v_mfma_f32_16x16x32_bf16 v[48:51], v[104:107], v[96:99], v[48:51]
	v_mfma_f32_16x16x32_bf16 v[16:19], v[104:107], v[0:3], v[84:87]
	s_waitcnt lgkmcnt(3)
	v_mfma_f32_16x16x32_bf16 v[44:47], v[110:113], v[96:99], v[88:91]
	v_mfma_f32_16x16x32_bf16 v[12:15], v[110:113], v[0:3], v[64:67]
	s_waitcnt lgkmcnt(2)
	v_mfma_f32_16x16x32_bf16 v[40:43], v[114:117], v[96:99], v[68:71]
	v_mfma_f32_16x16x32_bf16 v[8:11], v[114:117], v[0:3], v[72:75]
	s_waitcnt lgkmcnt(1)
	v_mfma_f32_16x16x32_bf16 v[36:39], v[118:121], v[96:99], v[76:79]
	v_mfma_f32_16x16x32_bf16 v[4:7], v[118:121], v[0:3], v[80:83]
	s_waitcnt lgkmcnt(0)
	v_mfma_f32_16x16x32_bf16 v[32:35], v[122:125], v[96:99], v[92:95]
	v_mfma_f32_16x16x32_bf16 v[0:3], v[122:125], v[0:3], v[100:103]
	s_setprio 1
	v_mov_b32_e32 v64, v60
	v_mov_b32_e32 v65, v56
	v_mov_b32_e32 v66, v61
	v_mov_b32_e32 v67, v57
	v_pk_add_f32 v[64:65], v[64:65], v[66:67]
	v_mov_b32_e32 v66, v62
	v_mov_b32_e32 v67, v58
	v_pk_add_f32 v[64:65], v[66:67], v[64:65]
	v_mov_b32_e32 v66, v63
	v_mov_b32_e32 v67, v59
	v_pk_add_f32 v[64:65], v[66:67], v[64:65]
	v_mov_b32_e32 v66, v53
	v_add_f32_e32 v64, 0, v64
	v_add_f32_e32 v68, v64, v65
	v_mov_b32_e32 v64, v52
	v_mov_b32_e32 v65, v48
	v_mov_b32_e32 v67, v49
	v_pk_add_f32 v[64:65], v[64:65], v[66:67]
	v_mov_b32_e32 v66, v54
	v_mov_b32_e32 v67, v50
	v_pk_add_f32 v[64:65], v[66:67], v[64:65]
	v_mov_b32_e32 v66, v55
	v_mov_b32_e32 v67, v51
	v_pk_add_f32 v[64:65], v[66:67], v[64:65]
	v_mov_b32_e32 v66, v45
	v_add_f32_e32 v64, v68, v64
	v_add_f32_e32 v68, v64, v65
	v_mov_b32_e32 v64, v44
	v_mov_b32_e32 v65, v40
	v_mov_b32_e32 v67, v41
	v_pk_add_f32 v[64:65], v[64:65], v[66:67]
	v_mov_b32_e32 v66, v46
	v_mov_b32_e32 v67, v42
	v_pk_add_f32 v[64:65], v[66:67], v[64:65]
	v_mov_b32_e32 v66, v47
	v_mov_b32_e32 v67, v43
	v_pk_add_f32 v[64:65], v[66:67], v[64:65]
	v_mov_b32_e32 v66, v37
	v_add_f32_e32 v64, v68, v64
	v_add_f32_e32 v68, v64, v65
	v_mov_b32_e32 v64, v36
	v_mov_b32_e32 v65, v32
	v_mov_b32_e32 v67, v33
	v_pk_add_f32 v[64:65], v[64:65], v[66:67]
	v_mov_b32_e32 v66, v38
	v_mov_b32_e32 v67, v34
	v_pk_add_f32 v[64:65], v[66:67], v[64:65]
	v_mov_b32_e32 v66, v39
	v_mov_b32_e32 v67, v35
	v_pk_add_f32 v[64:65], v[66:67], v[64:65]
	s_load_dwordx16 s[40:55], s[0:1], 0x100
	v_add_f32_e32 v64, v68, v64
	v_add_f32_e32 v64, v64, v65
	ds_bpermute_b32 v65, v109, v64
	s_lshl_b32 s2, s57, 2
	v_readlane_b32 s4, v241, 38
	s_add_u32 s30, s4, s2
	v_readlane_b32 s2, v241, 39
	s_waitcnt lgkmcnt(0)
	v_add_f32_e32 v65, v64, v65
	ds_bpermute_b32 v66, v154, v65
	v_add_u32_e32 v64, s66, v108
	s_addc_u32 s31, s2, 0
	s_lshl_b32 s96, s57, 1
	v_lshlrev_b32_e32 v128, 1, v156
	s_waitcnt lgkmcnt(0)
	v_add_f32_e32 v69, v65, v66
	v_ashrrev_i32_e32 v65, 31, v64
	v_lshlrev_b64 v[66:67], 14, v[64:65]
	v_lshl_add_u64 v[66:67], s[52:53], 0, v[66:67]
	v_lshl_add_u64 v[66:67], v[66:67], 0, s[96:97]
	v_lshl_add_u64 v[78:79], v[66:67], 0, v[128:129]
	s_movk_i32 s38, 0x1000
	v_add_co_u32_e32 v66, vcc, s38, v78
	v_lshlrev_b32_e32 v68, 2, v156
	s_nop 0
	v_addc_co_u32_e32 v67, vcc, 0, v79, vcc
	global_load_dwordx2 v[80:81], v[66:67], off offset:2048
	global_load_dwordx4 v[70:73], v68, s[30:31]
	v_fmamk_f32 v77, v69, 0xbc000000, v61
	v_fmamk_f32 v76, v69, 0xbc000000, v60
	v_mul_f32_e32 v75, v77, v77
	v_fmac_f32_e32 v75, v76, v76
	v_fmamk_f32 v62, v69, 0xbc000000, v62
	v_fmac_f32_e32 v75, v62, v62
	v_fmac_f32_e32 v63, 0xbc000000, v69
	v_fmac_f32_e32 v75, v63, v63
	v_fmamk_f32 v60, v69, 0xbc000000, v56
	v_fmac_f32_e32 v75, v60, v60
	v_fmamk_f32 v61, v69, 0xbc000000, v57
	v_fmac_f32_e32 v75, v61, v61
	v_fmamk_f32 v58, v69, 0xbc000000, v58
	v_fmac_f32_e32 v75, v58, v58
	v_fmac_f32_e32 v59, 0xbc000000, v69
	v_fmac_f32_e32 v75, v59, v59
	v_fmamk_f32 v82, v69, 0xbc000000, v52
	v_fmac_f32_e32 v75, v82, v82
	v_fmamk_f32 v83, v69, 0xbc000000, v53
	v_fmac_f32_e32 v75, v83, v83
	v_fmamk_f32 v54, v69, 0xbc000000, v54
	v_fmac_f32_e32 v75, v54, v54
	v_fmac_f32_e32 v55, 0xbc000000, v69
	v_fmac_f32_e32 v75, v55, v55
	v_fmamk_f32 v66, v69, 0xbc000000, v48
	v_fmac_f32_e32 v75, v66, v66
	v_fmamk_f32 v67, v69, 0xbc000000, v49
	v_fmac_f32_e32 v75, v67, v67
	v_fmamk_f32 v50, v69, 0xbc000000, v50
	v_fmac_f32_e32 v75, v50, v50
	v_fmac_f32_e32 v51, 0xbc000000, v69
	v_fmac_f32_e32 v75, v51, v51
	v_fmamk_f32 v56, v69, 0xbc000000, v44
	v_fmac_f32_e32 v75, v56, v56
	v_fmamk_f32 v57, v69, 0xbc000000, v45
	v_fmac_f32_e32 v75, v57, v57
	v_fmamk_f32 v46, v69, 0xbc000000, v46
	v_fmac_f32_e32 v75, v46, v46
	v_fmac_f32_e32 v47, 0xbc000000, v69
	v_fmac_f32_e32 v75, v47, v47
	v_fmamk_f32 v52, v69, 0xbc000000, v40
	v_fmac_f32_e32 v75, v52, v52
	v_fmamk_f32 v53, v69, 0xbc000000, v41
	v_fmac_f32_e32 v75, v53, v53
	v_fmamk_f32 v42, v69, 0xbc000000, v42
	v_fmac_f32_e32 v75, v42, v42
	v_fmac_f32_e32 v43, 0xbc000000, v69
	v_mul_f32_e32 v74, 0x3c000000, v69
	v_fmac_f32_e32 v75, v43, v43
	v_pk_add_f32 v[40:41], v[36:37], v[74:75] op_sel_hi:[1,0] neg_lo:[0,1] neg_hi:[0,1]
	s_mov_b32 s2, 0x800000
	v_pk_mul_f32 v[40:41], v[40:41], v[40:41]
	s_load_dwordx16 s[4:19], s[0:1], 0x140
	v_add_f32_e32 v40, v40, v75
	v_add_f32_e32 v44, v41, v40
	v_pk_add_f32 v[40:41], v[38:39], v[74:75] op_sel_hi:[1,0] neg_lo:[0,1] neg_hi:[0,1]
	s_mov_b64 s[40:41], 0x1800
	v_pk_mul_f32 v[40:41], v[40:41], v[40:41]
	v_fmamk_f32 v37, v69, 0xbc000000, v37
	v_add_f32_e32 v40, v40, v44
	v_add_f32_e32 v44, v41, v40
	v_pk_add_f32 v[40:41], v[32:33], v[74:75] op_sel_hi:[1,0] neg_lo:[0,1] neg_hi:[0,1]
	v_fmamk_f32 v36, v69, 0xbc000000, v36
	v_pk_mul_f32 v[40:41], v[40:41], v[40:41]
	v_fmamk_f32 v39, v69, 0xbc000000, v39
	v_add_f32_e32 v40, v40, v44
	v_add_f32_e32 v44, v41, v40
	v_pk_add_f32 v[40:41], v[34:35], v[74:75] op_sel_hi:[1,0] neg_lo:[0,1] neg_hi:[0,1]
	v_fmac_f32_e32 v38, 0xbc000000, v69
	v_pk_mul_f32 v[40:41], v[40:41], v[40:41]
	v_fmamk_f32 v33, v69, 0xbc000000, v33
	v_add_f32_e32 v40, v40, v44
	v_add_f32_e32 v40, v41, v40
	ds_bpermute_b32 v41, v109, v40
	v_fmamk_f32 v32, v69, 0xbc000000, v32
	v_fmamk_f32 v35, v69, 0xbc000000, v35
	v_fmac_f32_e32 v34, 0xbc000000, v69
	s_add_i32 s70, s70, s64
	s_waitcnt lgkmcnt(0)
	v_add_f32_e32 v40, v40, v41
	ds_bpermute_b32 v41, v154, v40
	s_waitcnt vmcnt(1)
	v_and_b32_e32 v45, 0xffff0000, v80
	v_lshlrev_b32_e32 v48, 16, v81
	v_and_b32_e32 v49, 0xffff0000, v81
	s_cmpk_gt_i32 s70, 0x41f
	s_waitcnt lgkmcnt(0)
	v_add_f32_e32 v40, v40, v41
	v_fmamk_f32 v40, v40, 0x3c000000, v163
	v_mul_f32_e32 v41, 0x4b800000, v40
	v_cmp_gt_f32_e32 vcc, s2, v40
	s_nop 1
	v_cndmask_b32_e32 v40, v40, v41, vcc
	v_rsq_f32_e32 v40, v40
	s_nop 0
	v_mul_f32_e32 v41, 0x45800000, v40
	v_cndmask_b32_e32 v40, v40, v41, vcc
	v_lshlrev_b32_e32 v41, 16, v80
	v_mul_f32_e32 v41, 0xbfb8aa3b, v41
	v_exp_f32_e32 v41, v41
	v_lshlrev_b64 v[80:81], 11, v[64:65]
	v_add_f32_e32 v41, 1.0, v41
	v_rcp_f32_e32 v44, v41
	v_mul_f32_e32 v41, 0xbfb8aa3b, v45
	v_mul_f32_e32 v45, 0xbfb8aa3b, v48
	v_exp_f32_e32 v45, v45
	v_mul_f32_e32 v48, 0xbfb8aa3b, v49
	v_exp_f32_e32 v41, v41
	v_exp_f32_e32 v48, v48
	v_add_f32_e32 v45, 1.0, v45
	v_rcp_f32_e32 v74, v45
	v_add_f32_e32 v41, 1.0, v41
	v_add_f32_e32 v45, 1.0, v48
	v_rcp_f32_e32 v75, v45
	v_rcp_f32_e32 v45, v41
	v_lshl_add_u64 v[48:49], v[78:79], 0, s[40:41]
	global_load_dwordx2 v[204:205], v[48:49], off offset:32
	global_load_dwordx2 v[206:207], v[48:49], off offset:64
	global_load_dwordx2 v[208:209], v[48:49], off offset:96
	global_load_dwordx2 v[210:211], v[48:49], off offset:128
	global_load_dwordx2 v[216:217], v[48:49], off offset:160
	global_load_dwordx2 v[218:219], v[48:49], off offset:192
	global_load_dwordx2 v[220:221], v[48:49], off offset:224
	global_load_dwordx4 v[224:227], v68, s[30:31] offset:64
	global_load_dwordx4 v[228:231], v68, s[30:31] offset:128
	global_load_dwordx4 v[232:235], v68, s[30:31] offset:192
	global_load_dwordx4 v[236:239], v68, s[30:31] offset:256
	v_mov_b32_e32 v78, v6
	v_pk_mul_f32 v[62:63], v[62:63], v[74:75]
	v_pk_mul_f32 v[44:45], v[76:77], v[44:45]
	v_pk_mul_f32 v[62:63], v[62:63], v[40:41] op_sel_hi:[1,0]
	v_pk_mul_f32 v[44:45], v[44:45], v[40:41] op_sel_hi:[1,0]
	s_waitcnt vmcnt(0)
	v_pk_mul_f32 v[62:63], v[72:73], v[62:63]
	v_pk_mul_f32 v[44:45], v[70:71], v[44:45]
	v_cvt_pk_bf16_f32 v71, v62, v63
	v_cvt_pk_bf16_f32 v70, v44, v45
	v_lshl_add_u64 v[44:45], s[10:11], 0, v[80:81]
	v_lshl_add_u64 v[44:45], v[44:45], 0, s[96:97]
	v_lshl_add_u64 v[44:45], v[44:45], 0, v[128:129]
	global_store_dwordx2 v[44:45], v[70:71], off
	v_mov_b32_e32 v62, v204
	v_mov_b32_e32 v63, v205
	s_nop 0
	v_mov_b32_e32 v70, v224
	v_mov_b32_e32 v71, v225
	v_mov_b32_e32 v72, v226
	v_mov_b32_e32 v73, v227
	v_mov_b32_e32 v76, v5
	v_mov_b32_e32 v77, v1
	v_mov_b32_e32 v79, v2
	v_mov_b32_e32 v80, v7
	v_mov_b32_e32 v81, v3
	v_lshlrev_b32_e32 v41, 16, v62
	v_mul_f32_e32 v41, 0xbfb8aa3b, v41
	v_exp_f32_e32 v41, v41
	v_and_b32_e32 v65, 0xffff0000, v62
	v_lshlrev_b32_e32 v74, 16, v63
	v_and_b32_e32 v63, 0xffff0000, v63
	v_add_f32_e32 v41, 1.0, v41
	v_rcp_f32_e32 v62, v41
	v_mul_f32_e32 v41, 0xbfb8aa3b, v65
	v_mul_f32_e32 v65, 0xbfb8aa3b, v74
	v_mul_f32_e32 v63, 0xbfb8aa3b, v63
	v_exp_f32_e32 v41, v41
	v_exp_f32_e32 v65, v65
	v_exp_f32_e32 v63, v63
	v_add_f32_e32 v41, 1.0, v41
	v_add_f32_e32 v65, 1.0, v65
	v_add_f32_e32 v63, 1.0, v63
	v_rcp_f32_e32 v74, v65
	v_rcp_f32_e32 v75, v63
	v_rcp_f32_e32 v63, v41
	v_pk_mul_f32 v[58:59], v[58:59], v[74:75]
	v_pk_mul_f32 v[60:61], v[60:61], v[62:63]
	v_pk_mul_f32 v[58:59], v[58:59], v[40:41] op_sel_hi:[1,0]
	v_pk_mul_f32 v[60:61], v[60:61], v[40:41] op_sel_hi:[1,0]
	v_pk_mul_f32 v[58:59], v[72:73], v[58:59]
	v_pk_mul_f32 v[60:61], v[70:71], v[60:61]
	v_mov_b32_e32 v73, v11
	v_cvt_pk_bf16_f32 v60, v60, v61
	v_cvt_pk_bf16_f32 v61, v58, v59
	global_store_dwordx2 v[44:45], v[60:61], off offset:32
	v_mov_b32_e32 v62, v206
	v_mov_b32_e32 v63, v207
	s_nop 0
	v_mov_b32_e32 v58, v228
	v_mov_b32_e32 v59, v229
	v_mov_b32_e32 v60, v230
	v_mov_b32_e32 v61, v231
	v_mov_b32_e32 v74, v4
	v_mov_b32_e32 v75, v0
	v_lshlrev_b32_e32 v41, 16, v62
	v_and_b32_e32 v62, 0xffff0000, v62
	v_lshlrev_b32_e32 v65, 16, v63
	v_and_b32_e32 v63, 0xffff0000, v63
	v_mul_f32_e32 v41, 0xbfb8aa3b, v41
	v_mul_f32_e32 v62, 0xbfb8aa3b, v62
	v_mul_f32_e32 v65, 0xbfb8aa3b, v65
	v_mul_f32_e32 v63, 0xbfb8aa3b, v63
	v_exp_f32_e32 v41, v41
	v_exp_f32_e32 v62, v62
	v_exp_f32_e32 v65, v65
	v_exp_f32_e32 v63, v63
	v_add_f32_e32 v41, 1.0, v41
	v_add_f32_e32 v72, 1.0, v62
	v_add_f32_e32 v65, 1.0, v65
	v_add_f32_e32 v63, 1.0, v63
	v_rcp_f32_e32 v62, v41
	v_rcp_f32_e32 v70, v65
	v_rcp_f32_e32 v71, v63
	v_rcp_f32_e32 v63, v72
	v_mov_b32_e32 v72, v15
	v_pk_mul_f32 v[54:55], v[54:55], v[70:71]
	v_pk_mul_f32 v[62:63], v[82:83], v[62:63]
	v_pk_mul_f32 v[54:55], v[54:55], v[40:41] op_sel_hi:[1,0]
	v_pk_mul_f32 v[62:63], v[62:63], v[40:41] op_sel_hi:[1,0]
	v_pk_mul_f32 v[54:55], v[60:61], v[54:55]
	v_pk_mul_f32 v[58:59], v[58:59], v[62:63]
	v_mov_b32_e32 v70, v14
	v_cvt_pk_bf16_f32 v58, v58, v59
	v_cvt_pk_bf16_f32 v59, v54, v55
	global_store_dwordx2 v[44:45], v[58:59], off offset:64
	v_mov_b32_e32 v54, v208
	v_mov_b32_e32 v55, v209
	s_nop 0
	v_mov_b32_e32 v58, v232
	v_mov_b32_e32 v59, v233
	v_mov_b32_e32 v60, v234
	v_mov_b32_e32 v61, v235
	v_mov_b32_e32 v71, v10
	v_lshlrev_b32_e32 v41, 16, v54
	v_and_b32_e32 v54, 0xffff0000, v54
	v_lshlrev_b32_e32 v62, 16, v55
	v_and_b32_e32 v55, 0xffff0000, v55
	v_mul_f32_e32 v41, 0xbfb8aa3b, v41
	v_mul_f32_e32 v54, 0xbfb8aa3b, v54
	v_mul_f32_e32 v62, 0xbfb8aa3b, v62
	v_mul_f32_e32 v55, 0xbfb8aa3b, v55
	v_exp_f32_e32 v41, v41
	v_exp_f32_e32 v54, v54
	v_exp_f32_e32 v62, v62
	v_exp_f32_e32 v55, v55
	v_add_f32_e32 v41, 1.0, v41
	v_add_f32_e32 v65, 1.0, v54
	v_add_f32_e32 v62, 1.0, v62
	v_add_f32_e32 v55, 1.0, v55
	v_rcp_f32_e32 v54, v41
	v_rcp_f32_e32 v62, v62
	v_rcp_f32_e32 v63, v55
	v_rcp_f32_e32 v55, v65
	v_pk_mul_f32 v[50:51], v[50:51], v[62:63]
	v_pk_mul_f32 v[54:55], v[66:67], v[54:55]
	v_pk_mul_f32 v[50:51], v[50:51], v[40:41] op_sel_hi:[1,0]
	v_pk_mul_f32 v[54:55], v[54:55], v[40:41] op_sel_hi:[1,0]
	v_pk_mul_f32 v[50:51], v[60:61], v[50:51]
	v_pk_mul_f32 v[54:55], v[58:59], v[54:55]
	v_mov_b32_e32 v63, v8
	v_cvt_pk_bf16_f32 v54, v54, v55
	v_cvt_pk_bf16_f32 v55, v50, v51
	global_store_dwordx2 v[44:45], v[54:55], off offset:96
	v_mov_b32_e32 v50, v210
	v_mov_b32_e32 v51, v211
	v_mov_b32_e32 v58, v236
	v_mov_b32_e32 v59, v237
	v_mov_b32_e32 v60, v238
	v_mov_b32_e32 v61, v239
	v_mov_b32_e32 v66, v13
	v_mov_b32_e32 v67, v9
	v_lshlrev_b32_e32 v41, 16, v50
	v_and_b32_e32 v50, 0xffff0000, v50
	v_lshlrev_b32_e32 v54, 16, v51
	v_and_b32_e32 v51, 0xffff0000, v51
	v_mul_f32_e32 v41, 0xbfb8aa3b, v41
	v_mul_f32_e32 v50, 0xbfb8aa3b, v50
	v_mul_f32_e32 v54, 0xbfb8aa3b, v54
	v_mul_f32_e32 v51, 0xbfb8aa3b, v51
	v_exp_f32_e32 v41, v41
	v_exp_f32_e32 v50, v50
	v_exp_f32_e32 v54, v54
	v_exp_f32_e32 v51, v51
	v_add_f32_e32 v41, 1.0, v41
	v_add_f32_e32 v62, 1.0, v50
	v_add_f32_e32 v54, 1.0, v54
	v_add_f32_e32 v51, 1.0, v51
	v_rcp_f32_e32 v50, v41
	v_rcp_f32_e32 v54, v54
	v_rcp_f32_e32 v55, v51
	v_rcp_f32_e32 v51, v62
	v_mov_b32_e32 v62, v12
	v_pk_mul_f32 v[46:47], v[46:47], v[54:55]
	v_pk_mul_f32 v[50:51], v[56:57], v[50:51]
	v_pk_mul_f32 v[46:47], v[46:47], v[40:41] op_sel_hi:[1,0]
	v_pk_mul_f32 v[50:51], v[50:51], v[40:41] op_sel_hi:[1,0]
	v_pk_mul_f32 v[46:47], v[60:61], v[46:47]
	v_pk_mul_f32 v[50:51], v[58:59], v[50:51]
	v_mov_b32_e32 v59, v18
	v_cvt_pk_bf16_f32 v50, v50, v51
	v_cvt_pk_bf16_f32 v51, v46, v47
	global_store_dwordx2 v[44:45], v[50:51], off offset:128
	v_mov_b32_e32 v46, v216
	v_mov_b32_e32 v47, v217
	global_load_dwordx4 v[54:57], v68, s[30:31] offset:320
	v_mov_b32_e32 v60, v23
	v_mov_b32_e32 v61, v19
	v_lshlrev_b32_e32 v41, 16, v46
	v_and_b32_e32 v46, 0xffff0000, v46
	v_lshlrev_b32_e32 v50, 16, v47
	v_and_b32_e32 v47, 0xffff0000, v47
	v_mul_f32_e32 v41, 0xbfb8aa3b, v41
	v_mul_f32_e32 v46, 0xbfb8aa3b, v46
	v_mul_f32_e32 v50, 0xbfb8aa3b, v50
	v_mul_f32_e32 v47, 0xbfb8aa3b, v47
	v_exp_f32_e32 v41, v41
	v_exp_f32_e32 v46, v46
	v_exp_f32_e32 v50, v50
	v_exp_f32_e32 v47, v47
	v_add_f32_e32 v41, 1.0, v41
	v_add_f32_e32 v58, 1.0, v46
	v_add_f32_e32 v50, 1.0, v50
	v_add_f32_e32 v47, 1.0, v47
	v_rcp_f32_e32 v46, v41
	v_rcp_f32_e32 v50, v50
	v_rcp_f32_e32 v51, v47
	v_rcp_f32_e32 v47, v58
	v_mov_b32_e32 v58, v22
	v_pk_mul_f32 v[42:43], v[42:43], v[50:51]
	v_pk_mul_f32 v[46:47], v[52:53], v[46:47]
	v_pk_mul_f32 v[42:43], v[40:41], v[42:43] op_sel_hi:[0,1]
	v_pk_mul_f32 v[46:47], v[40:41], v[46:47] op_sel_hi:[0,1]
	s_waitcnt vmcnt(0)
	v_pk_mul_f32 v[42:43], v[56:57], v[42:43]
	v_pk_mul_f32 v[46:47], v[54:55], v[46:47]
	v_mov_b32_e32 v55, v16
	v_cvt_pk_bf16_f32 v46, v46, v47
	v_cvt_pk_bf16_f32 v47, v42, v43
	global_store_dwordx2 v[44:45], v[46:47], off offset:160
	v_mov_b32_e32 v42, v218
	v_mov_b32_e32 v43, v219
	global_load_dwordx4 v[50:53], v68, s[30:31] offset:384
	v_mov_b32_e32 v56, v21
	v_mov_b32_e32 v57, v17
	v_lshlrev_b32_e32 v41, 16, v42
	v_and_b32_e32 v42, 0xffff0000, v42
	v_lshlrev_b32_e32 v46, 16, v43
	v_and_b32_e32 v43, 0xffff0000, v43
	v_mul_f32_e32 v41, 0xbfb8aa3b, v41
	v_mul_f32_e32 v42, 0xbfb8aa3b, v42
	v_mul_f32_e32 v46, 0xbfb8aa3b, v46
	v_mul_f32_e32 v43, 0xbfb8aa3b, v43
	v_exp_f32_e32 v41, v41
	v_exp_f32_e32 v42, v42
	v_exp_f32_e32 v46, v46
	v_exp_f32_e32 v43, v43
	v_add_f32_e32 v41, 1.0, v41
	v_add_f32_e32 v54, 1.0, v42
	v_add_f32_e32 v46, 1.0, v46
	v_add_f32_e32 v43, 1.0, v43
	v_rcp_f32_e32 v42, v41
	v_rcp_f32_e32 v46, v46
	v_rcp_f32_e32 v47, v43
	v_rcp_f32_e32 v43, v54
	v_mov_b32_e32 v54, v20
	v_pk_mul_f32 v[38:39], v[38:39], v[46:47]
	v_pk_mul_f32 v[36:37], v[36:37], v[42:43]
	v_pk_mul_f32 v[38:39], v[40:41], v[38:39] op_sel_hi:[0,1]
	v_pk_mul_f32 v[36:37], v[40:41], v[36:37] op_sel_hi:[0,1]
	s_waitcnt vmcnt(0)
	v_pk_mul_f32 v[38:39], v[52:53], v[38:39]
	v_pk_mul_f32 v[36:37], v[50:51], v[36:37]
	v_mov_b32_e32 v42, v29
	v_cvt_pk_bf16_f32 v36, v36, v37
	v_cvt_pk_bf16_f32 v37, v38, v39
	global_store_dwordx2 v[44:45], v[36:37], off offset:192
	v_mov_b32_e32 v36, v220
	v_mov_b32_e32 v37, v221
	v_mov_b32_e32 v38, v28
	global_load_dwordx4 v[46:49], v68, s[30:31] offset:448
	v_mov_b32_e32 v39, v24
	v_mov_b32_e32 v43, v25
	v_mov_b32_e32 v50, v30
	v_mov_b32_e32 v51, v26
	v_pk_add_f32 v[38:39], v[38:39], v[42:43]
	v_mov_b32_e32 v52, v31
	v_mov_b32_e32 v53, v27
	v_pk_add_f32 v[38:39], v[50:51], v[38:39]
	v_pk_add_f32 v[42:43], v[54:55], v[56:57]
	v_pk_add_f32 v[38:39], v[52:53], v[38:39]
	v_pk_add_f32 v[42:43], v[58:59], v[42:43]
	v_add_f32_e32 v38, 0, v38
	v_pk_add_f32 v[54:55], v[62:63], v[66:67]
	v_pk_add_f32 v[42:43], v[60:61], v[42:43]
	v_add_f32_e32 v38, v38, v39
	v_pk_add_f32 v[50:51], v[70:71], v[54:55]
	v_add_f32_e32 v38, v38, v42
	v_pk_add_f32 v[56:57], v[74:75], v[76:77]
	v_pk_add_f32 v[50:51], v[72:73], v[50:51]
	v_add_f32_e32 v38, v38, v43
	v_pk_add_f32 v[54:55], v[78:79], v[56:57]
	v_add_f32_e32 v38, v38, v50
	v_pk_add_f32 v[52:53], v[80:81], v[54:55]
	v_add_f32_e32 v38, v38, v51
	v_add_f32_e32 v38, v38, v52
	v_add_f32_e32 v41, v38, v53
	v_add_u32_e32 v62, 16, v64
	ds_bpermute_b32 v50, v109, v41
	v_ashrrev_i32_e32 v63, 31, v62
	v_lshlrev_b64 v[38:39], 14, v[62:63]
	v_lshl_add_u64 v[38:39], s[52:53], 0, v[38:39]
	v_lshl_add_u64 v[38:39], v[38:39], 0, s[96:97]
	v_lshl_add_u64 v[42:43], v[38:39], 0, v[128:129]
	s_waitcnt lgkmcnt(0)
	v_add_f32_e32 v38, v41, v50
	ds_bpermute_b32 v39, v154, v38
	v_add_co_u32_e32 v50, vcc, s38, v42
	s_waitcnt lgkmcnt(0)
	v_add_f32_e32 v38, v38, v39
	v_fmamk_f32 v54, v38, 0xbc000000, v28
	v_fmamk_f32 v55, v38, 0xbc000000, v29
	v_addc_co_u32_e32 v51, vcc, 0, v43, vcc
	v_mul_f32_e32 v39, v55, v55
	v_fmamk_f32 v30, v38, 0xbc000000, v30
	v_fmac_f32_e32 v39, v54, v54
	v_fmac_f32_e32 v31, 0xbc000000, v38
	v_fmac_f32_e32 v39, v30, v30
	v_fmac_f32_e32 v39, v31, v31
	v_fmamk_f32 v26, v38, 0xbc000000, v26
	v_fmac_f32_e32 v27, 0xbc000000, v38
	v_fmamk_f32 v22, v38, 0xbc000000, v22
	v_fmac_f32_e32 v23, 0xbc000000, v38
	v_fmamk_f32 v18, v38, 0xbc000000, v18
	v_fmac_f32_e32 v19, 0xbc000000, v38
	v_fmamk_f32 v14, v38, 0xbc000000, v14
	v_fmac_f32_e32 v15, 0xbc000000, v38
	v_mul_f32_e32 v52, 0x3c000000, v38
	v_fmamk_f32 v10, v38, 0xbc000000, v10
	v_fmac_f32_e32 v11, 0xbc000000, v38
	v_lshlrev_b32_e32 v28, 16, v36
	v_and_b32_e32 v29, 0xffff0000, v36
	v_lshlrev_b32_e32 v36, 16, v37
	v_and_b32_e32 v37, 0xffff0000, v37
	v_mul_f32_e32 v28, 0xbfb8aa3b, v28
	v_mul_f32_e32 v29, 0xbfb8aa3b, v29
	v_mul_f32_e32 v36, 0xbfb8aa3b, v36
	v_mul_f32_e32 v37, 0xbfb8aa3b, v37
	v_exp_f32_e32 v28, v28
	v_exp_f32_e32 v29, v29
	v_exp_f32_e32 v36, v36
	v_exp_f32_e32 v37, v37
	v_add_f32_e32 v28, 1.0, v28
	v_add_f32_e32 v29, 1.0, v29
	v_add_f32_e32 v36, 1.0, v36
	v_add_f32_e32 v37, 1.0, v37
	v_rcp_f32_e32 v28, v28
	v_rcp_f32_e32 v36, v36
	v_rcp_f32_e32 v37, v37
	v_rcp_f32_e32 v29, v29
	v_pk_mul_f32 v[34:35], v[34:35], v[36:37]
	v_pk_mul_f32 v[28:29], v[32:33], v[28:29]
	v_pk_mul_f32 v[32:33], v[40:41], v[34:35] op_sel_hi:[0,1]
	v_pk_mul_f32 v[28:29], v[40:41], v[28:29] op_sel_hi:[0,1]
	s_waitcnt vmcnt(0)
	v_pk_mul_f32 v[32:33], v[48:49], v[32:33]
	v_pk_mul_f32 v[28:29], v[46:47], v[28:29]
	v_pk_add_f32 v[46:47], v[2:3], v[52:53] op_sel_hi:[1,0] neg_lo:[0,1] neg_hi:[0,1]
	v_cvt_pk_bf16_f32 v28, v28, v29
	v_cvt_pk_bf16_f32 v29, v32, v33
	global_store_dwordx2 v[44:45], v[28:29], off offset:224
	global_load_dwordx2 v[40:41], v[50:51], off offset:2048
	global_load_dwordx4 v[34:37], v68, s[30:31]
	v_fmamk_f32 v44, v38, 0xbc000000, v24
	v_fmamk_f32 v45, v38, 0xbc000000, v25
	v_fmac_f32_e32 v39, v44, v44
	v_fmac_f32_e32 v39, v45, v45
	v_fmac_f32_e32 v39, v26, v26
	v_fmamk_f32 v32, v38, 0xbc000000, v20
	v_fmac_f32_e32 v39, v27, v27
	v_fmamk_f32 v33, v38, 0xbc000000, v21
	v_fmac_f32_e32 v39, v32, v32
	v_fmac_f32_e32 v39, v33, v33
	v_fmac_f32_e32 v39, v22, v22
	v_fmamk_f32 v28, v38, 0xbc000000, v16
	v_fmac_f32_e32 v39, v23, v23
	v_fmamk_f32 v29, v38, 0xbc000000, v17
	v_fmac_f32_e32 v39, v28, v28
	v_fmac_f32_e32 v39, v29, v29
	v_fmac_f32_e32 v39, v18, v18
	v_fmamk_f32 v24, v38, 0xbc000000, v12
	v_fmac_f32_e32 v39, v19, v19
	v_fmamk_f32 v25, v38, 0xbc000000, v13
	v_fmac_f32_e32 v39, v24, v24
	v_fmac_f32_e32 v39, v25, v25
	v_fmac_f32_e32 v39, v14, v14
	v_fmamk_f32 v16, v38, 0xbc000000, v8
	v_fmac_f32_e32 v39, v15, v15
	v_fmamk_f32 v17, v38, 0xbc000000, v9
	v_fmac_f32_e32 v39, v16, v16
	v_fmac_f32_e32 v39, v17, v17
	v_pk_add_f32 v[8:9], v[4:5], v[52:53] op_sel_hi:[1,0] neg_lo:[0,1] neg_hi:[0,1]
	v_fmac_f32_e32 v39, v10, v10
	v_pk_mul_f32 v[8:9], v[8:9], v[8:9]
	v_fmac_f32_e32 v39, v11, v11
	v_pk_add_f32 v[12:13], v[6:7], v[52:53] op_sel_hi:[1,0] neg_lo:[0,1] neg_hi:[0,1]
	v_add_f32_e32 v8, v8, v39
	v_pk_mul_f32 v[12:13], v[12:13], v[12:13]
	v_add_f32_e32 v8, v9, v8
	v_pk_add_f32 v[20:21], v[0:1], v[52:53] op_sel_hi:[1,0] neg_lo:[0,1] neg_hi:[0,1]
	v_add_f32_e32 v8, v12, v8
	v_pk_mul_f32 v[20:21], v[20:21], v[20:21]
	v_add_f32_e32 v8, v13, v8
	v_add_f32_e32 v8, v20, v8
	v_pk_mul_f32 v[46:47], v[46:47], v[46:47]
	v_add_f32_e32 v8, v21, v8
	v_add_f32_e32 v8, v46, v8
	v_add_f32_e32 v12, v47, v8
	ds_bpermute_b32 v13, v109, v12
	v_lshl_add_u64 v[20:21], v[42:43], 0, s[40:41]
	global_load_dwordx2 v[222:223], v[20:21], off offset:32
	global_load_dwordx2 v[224:225], v[20:21], off offset:64
	global_load_dwordx2 v[226:227], v[20:21], off offset:96
	global_load_dwordx2 v[228:229], v[20:21], off offset:128
	global_load_dwordx2 v[230:231], v[20:21], off offset:160
	global_load_dwordx2 v[232:233], v[20:21], off offset:192
	global_load_dwordx2 v[234:235], v[20:21], off offset:224
	global_load_dwordx4 v[204:207], v68, s[30:31] offset:64
	global_load_dwordx4 v[208:211], v68, s[30:31] offset:128
	global_load_dwordx4 v[216:219], v68, s[30:31] offset:192
	global_load_dwordx4 v[236:239], v68, s[30:31] offset:256
	v_lshlrev_b64 v[8:9], 11, v[62:63]
	v_lshl_add_u64 v[8:9], s[10:11], 0, v[8:9]
	v_lshl_add_u64 v[8:9], v[8:9], 0, s[96:97]
	s_waitcnt lgkmcnt(0)
	v_add_f32_e32 v12, v12, v13
	ds_bpermute_b32 v13, v154, v12
	v_lshl_add_u64 v[8:9], v[8:9], 0, v[128:129]
	v_fmamk_f32 v5, v38, 0xbc000000, v5
	v_fmamk_f32 v4, v38, 0xbc000000, v4
	v_fmamk_f32 v7, v38, 0xbc000000, v7
	s_waitcnt lgkmcnt(0)
	v_add_f32_e32 v12, v12, v13
	v_fmamk_f32 v12, v12, 0x3c000000, v163
	v_mul_f32_e32 v13, 0x4b800000, v12
	v_cmp_gt_f32_e32 vcc, s2, v12
	v_fmac_f32_e32 v6, 0xbc000000, v38
	v_fmamk_f32 v1, v38, 0xbc000000, v1
	v_cndmask_b32_e32 v12, v12, v13, vcc
	v_rsq_f32_e32 v12, v12
	v_fmamk_f32 v0, v38, 0xbc000000, v0
	v_fmamk_f32 v3, v38, 0xbc000000, v3
	v_fmac_f32_e32 v2, 0xbc000000, v38
	s_waitcnt vmcnt(1)
	v_lshlrev_b32_e32 v13, 16, v40
	v_and_b32_e32 v39, 0xffff0000, v40
	v_lshlrev_b32_e32 v40, 16, v41
	v_and_b32_e32 v41, 0xffff0000, v41
	v_mul_f32_e32 v13, 0xbfb8aa3b, v13
	v_mul_f32_e32 v39, 0xbfb8aa3b, v39
	v_mul_f32_e32 v40, 0xbfb8aa3b, v40
	v_mul_f32_e32 v41, 0xbfb8aa3b, v41
	v_exp_f32_e32 v13, v13
	v_exp_f32_e32 v39, v39
	v_exp_f32_e32 v40, v40
	v_exp_f32_e32 v41, v41
	v_add_f32_e32 v13, 1.0, v13
	v_add_f32_e32 v39, 1.0, v39
	v_add_f32_e32 v42, 1.0, v40
	v_add_f32_e32 v41, 1.0, v41
	v_rcp_f32_e32 v40, v13
	v_rcp_f32_e32 v42, v42
	v_rcp_f32_e32 v43, v41
	v_rcp_f32_e32 v41, v39
	v_mul_f32_e32 v13, 0x45800000, v12
	v_cndmask_b32_e32 v12, v12, v13, vcc
	v_pk_mul_f32 v[30:31], v[30:31], v[42:43]
	v_pk_mul_f32 v[40:41], v[54:55], v[40:41]
	v_pk_mul_f32 v[30:31], v[30:31], v[12:13] op_sel_hi:[1,0]
	v_pk_mul_f32 v[40:41], v[40:41], v[12:13] op_sel_hi:[1,0]
	s_waitcnt vmcnt(0)
	v_pk_mul_f32 v[30:31], v[36:37], v[30:31]
	v_pk_mul_f32 v[34:35], v[34:35], v[40:41]
	s_nop 0
	v_cvt_pk_bf16_f32 v34, v34, v35
	v_cvt_pk_bf16_f32 v35, v30, v31
	global_store_dwordx2 v[8:9], v[34:35], off
	v_mov_b32_e32 v30, v222
	v_mov_b32_e32 v31, v223
	s_nop 0
	v_mov_b32_e32 v34, v204
	v_mov_b32_e32 v35, v205
	v_mov_b32_e32 v36, v206
	v_mov_b32_e32 v37, v207
	v_lshlrev_b32_e32 v13, 16, v30
	v_and_b32_e32 v30, 0xffff0000, v30
	v_lshlrev_b32_e32 v39, 16, v31
	v_and_b32_e32 v31, 0xffff0000, v31
	v_mul_f32_e32 v13, 0xbfb8aa3b, v13
	v_mul_f32_e32 v30, 0xbfb8aa3b, v30
	v_mul_f32_e32 v39, 0xbfb8aa3b, v39
	v_mul_f32_e32 v31, 0xbfb8aa3b, v31
	v_exp_f32_e32 v13, v13
	v_exp_f32_e32 v30, v30
	v_exp_f32_e32 v39, v39
	v_exp_f32_e32 v31, v31
	v_add_f32_e32 v13, 1.0, v13
	v_add_f32_e32 v42, 1.0, v30
	v_add_f32_e32 v39, 1.0, v39
	v_add_f32_e32 v31, 1.0, v31
	v_rcp_f32_e32 v30, v13
	v_rcp_f32_e32 v40, v39
	v_rcp_f32_e32 v41, v31
	v_rcp_f32_e32 v31, v42
	v_pk_mul_f32 v[26:27], v[26:27], v[40:41]
	v_pk_mul_f32 v[30:31], v[44:45], v[30:31]
	v_pk_mul_f32 v[26:27], v[26:27], v[12:13] op_sel_hi:[1,0]
	v_pk_mul_f32 v[30:31], v[30:31], v[12:13] op_sel_hi:[1,0]
	v_pk_mul_f32 v[26:27], v[36:37], v[26:27]
	v_pk_mul_f32 v[30:31], v[34:35], v[30:31]
	s_nop 0
	v_cvt_pk_bf16_f32 v30, v30, v31
	v_cvt_pk_bf16_f32 v31, v26, v27
	global_store_dwordx2 v[8:9], v[30:31], off offset:32
	v_mov_b32_e32 v26, v224
	v_mov_b32_e32 v27, v225
	v_mov_b32_e32 v34, v208
	v_mov_b32_e32 v35, v209
	v_mov_b32_e32 v36, v210
	v_mov_b32_e32 v37, v211
	v_lshlrev_b32_e32 v13, 16, v26
	v_and_b32_e32 v26, 0xffff0000, v26
	v_lshlrev_b32_e32 v30, 16, v27
	v_and_b32_e32 v27, 0xffff0000, v27
	v_mul_f32_e32 v13, 0xbfb8aa3b, v13
	v_mul_f32_e32 v26, 0xbfb8aa3b, v26
	v_mul_f32_e32 v30, 0xbfb8aa3b, v30
	v_mul_f32_e32 v27, 0xbfb8aa3b, v27
	v_exp_f32_e32 v13, v13
	v_exp_f32_e32 v26, v26
	v_exp_f32_e32 v30, v30
	v_exp_f32_e32 v27, v27
	v_add_f32_e32 v13, 1.0, v13
	v_add_f32_e32 v39, 1.0, v26
	v_add_f32_e32 v30, 1.0, v30
	v_add_f32_e32 v27, 1.0, v27
	v_rcp_f32_e32 v26, v13
	v_rcp_f32_e32 v30, v30
	v_rcp_f32_e32 v31, v27
	v_rcp_f32_e32 v27, v39
	v_pk_mul_f32 v[22:23], v[22:23], v[30:31]
	v_pk_mul_f32 v[26:27], v[32:33], v[26:27]
	v_pk_mul_f32 v[22:23], v[22:23], v[12:13] op_sel_hi:[1,0]
	v_pk_mul_f32 v[26:27], v[26:27], v[12:13] op_sel_hi:[1,0]
	v_pk_mul_f32 v[22:23], v[36:37], v[22:23]
	v_pk_mul_f32 v[26:27], v[34:35], v[26:27]
	s_nop 0
	v_cvt_pk_bf16_f32 v26, v26, v27
	v_cvt_pk_bf16_f32 v27, v22, v23
	global_store_dwordx2 v[8:9], v[26:27], off offset:64
	v_mov_b32_e32 v22, v226
	v_mov_b32_e32 v23, v227
	v_mov_b32_e32 v30, v216
	v_mov_b32_e32 v31, v217
	v_mov_b32_e32 v32, v218
	v_mov_b32_e32 v33, v219
	v_lshlrev_b32_e32 v13, 16, v22
	v_and_b32_e32 v22, 0xffff0000, v22
	v_lshlrev_b32_e32 v26, 16, v23
	v_and_b32_e32 v23, 0xffff0000, v23
	v_mul_f32_e32 v13, 0xbfb8aa3b, v13
	v_mul_f32_e32 v22, 0xbfb8aa3b, v22
	v_mul_f32_e32 v26, 0xbfb8aa3b, v26
	v_mul_f32_e32 v23, 0xbfb8aa3b, v23
	v_exp_f32_e32 v13, v13
	v_exp_f32_e32 v22, v22
	v_exp_f32_e32 v26, v26
	v_exp_f32_e32 v23, v23
	v_add_f32_e32 v13, 1.0, v13
	v_add_f32_e32 v34, 1.0, v22
	v_add_f32_e32 v26, 1.0, v26
	v_add_f32_e32 v23, 1.0, v23
	v_rcp_f32_e32 v22, v13
	v_rcp_f32_e32 v26, v26
	v_rcp_f32_e32 v27, v23
	v_rcp_f32_e32 v23, v34
	v_pk_mul_f32 v[18:19], v[18:19], v[26:27]
	v_pk_mul_f32 v[22:23], v[28:29], v[22:23]
	v_pk_mul_f32 v[18:19], v[18:19], v[12:13] op_sel_hi:[1,0]
	v_pk_mul_f32 v[22:23], v[22:23], v[12:13] op_sel_hi:[1,0]
	v_pk_mul_f32 v[18:19], v[32:33], v[18:19]
	v_pk_mul_f32 v[22:23], v[30:31], v[22:23]
	s_nop 0
	v_cvt_pk_bf16_f32 v22, v22, v23
	v_cvt_pk_bf16_f32 v23, v18, v19
	global_store_dwordx2 v[8:9], v[22:23], off offset:96
	v_mov_b32_e32 v18, v228
	v_mov_b32_e32 v19, v229
	v_mov_b32_e32 v26, v236
	v_mov_b32_e32 v27, v237
	v_mov_b32_e32 v28, v238
	v_mov_b32_e32 v29, v239
	v_lshlrev_b32_e32 v13, 16, v18
	v_and_b32_e32 v18, 0xffff0000, v18
	v_lshlrev_b32_e32 v22, 16, v19
	v_and_b32_e32 v19, 0xffff0000, v19
	v_mul_f32_e32 v13, 0xbfb8aa3b, v13
	v_mul_f32_e32 v18, 0xbfb8aa3b, v18
	v_mul_f32_e32 v22, 0xbfb8aa3b, v22
	v_mul_f32_e32 v19, 0xbfb8aa3b, v19
	v_exp_f32_e32 v13, v13
	v_exp_f32_e32 v18, v18
	v_exp_f32_e32 v22, v22
	v_exp_f32_e32 v19, v19
	v_add_f32_e32 v13, 1.0, v13
	v_add_f32_e32 v30, 1.0, v18
	v_add_f32_e32 v22, 1.0, v22
	v_add_f32_e32 v19, 1.0, v19
	v_rcp_f32_e32 v18, v13
	v_rcp_f32_e32 v22, v22
	v_rcp_f32_e32 v23, v19
	v_rcp_f32_e32 v19, v30
	v_pk_mul_f32 v[14:15], v[14:15], v[22:23]
	v_pk_mul_f32 v[18:19], v[24:25], v[18:19]
	v_pk_mul_f32 v[14:15], v[14:15], v[12:13] op_sel_hi:[1,0]
	v_pk_mul_f32 v[18:19], v[18:19], v[12:13] op_sel_hi:[1,0]
	v_pk_mul_f32 v[14:15], v[28:29], v[14:15]
	v_pk_mul_f32 v[18:19], v[26:27], v[18:19]
	s_nop 0
	v_cvt_pk_bf16_f32 v18, v18, v19
	v_cvt_pk_bf16_f32 v19, v14, v15
	global_store_dwordx2 v[8:9], v[18:19], off offset:128
	v_mov_b32_e32 v14, v230
	v_mov_b32_e32 v15, v231
	global_load_dwordx4 v[22:25], v68, s[30:31] offset:320
	v_lshlrev_b32_e32 v13, 16, v14
	v_and_b32_e32 v14, 0xffff0000, v14
	v_lshlrev_b32_e32 v18, 16, v15
	v_and_b32_e32 v15, 0xffff0000, v15
	v_mul_f32_e32 v13, 0xbfb8aa3b, v13
	v_mul_f32_e32 v14, 0xbfb8aa3b, v14
	v_mul_f32_e32 v18, 0xbfb8aa3b, v18
	v_mul_f32_e32 v15, 0xbfb8aa3b, v15
	v_exp_f32_e32 v13, v13
	v_exp_f32_e32 v14, v14
	v_exp_f32_e32 v18, v18
	v_exp_f32_e32 v15, v15
	v_add_f32_e32 v13, 1.0, v13
	v_add_f32_e32 v26, 1.0, v14
	v_add_f32_e32 v18, 1.0, v18
	v_add_f32_e32 v15, 1.0, v15
	v_rcp_f32_e32 v14, v13
	v_rcp_f32_e32 v18, v18
	v_rcp_f32_e32 v19, v15
	v_rcp_f32_e32 v15, v26
	v_pk_mul_f32 v[10:11], v[10:11], v[18:19]
	v_pk_mul_f32 v[14:15], v[16:17], v[14:15]
	v_pk_mul_f32 v[10:11], v[12:13], v[10:11] op_sel_hi:[0,1]
	v_pk_mul_f32 v[14:15], v[12:13], v[14:15] op_sel_hi:[0,1]
	s_waitcnt vmcnt(0)
	v_pk_mul_f32 v[10:11], v[24:25], v[10:11]
	v_pk_mul_f32 v[14:15], v[22:23], v[14:15]
	s_nop 0
	v_cvt_pk_bf16_f32 v14, v14, v15
	v_cvt_pk_bf16_f32 v15, v10, v11
	global_store_dwordx2 v[8:9], v[14:15], off offset:160
	v_mov_b32_e32 v10, v232
	v_mov_b32_e32 v11, v233
	s_nop 0
	global_load_dwordx4 v[14:17], v68, s[30:31] offset:384
	v_lshlrev_b32_e32 v13, 16, v10
	v_and_b32_e32 v10, 0xffff0000, v10
	v_lshlrev_b32_e32 v18, 16, v11
	v_and_b32_e32 v11, 0xffff0000, v11
	v_mul_f32_e32 v13, 0xbfb8aa3b, v13
	v_mul_f32_e32 v10, 0xbfb8aa3b, v10
	v_mul_f32_e32 v18, 0xbfb8aa3b, v18
	v_mul_f32_e32 v11, 0xbfb8aa3b, v11
	v_exp_f32_e32 v13, v13
	v_exp_f32_e32 v10, v10
	v_exp_f32_e32 v18, v18
	v_exp_f32_e32 v11, v11
	v_add_f32_e32 v13, 1.0, v13
	v_add_f32_e32 v22, 1.0, v10
	v_add_f32_e32 v18, 1.0, v18
	v_add_f32_e32 v11, 1.0, v11
	v_rcp_f32_e32 v10, v13
	v_rcp_f32_e32 v18, v18
	v_rcp_f32_e32 v19, v11
	v_rcp_f32_e32 v11, v22
	v_pk_mul_f32 v[6:7], v[6:7], v[18:19]
	v_pk_mul_f32 v[4:5], v[4:5], v[10:11]
	v_pk_mul_f32 v[6:7], v[12:13], v[6:7] op_sel_hi:[0,1]
	v_pk_mul_f32 v[4:5], v[12:13], v[4:5] op_sel_hi:[0,1]
	s_waitcnt vmcnt(0)
	v_pk_mul_f32 v[6:7], v[16:17], v[6:7]
	v_pk_mul_f32 v[4:5], v[14:15], v[4:5]
	s_nop 0
	v_cvt_pk_bf16_f32 v4, v4, v5
	v_cvt_pk_bf16_f32 v5, v6, v7
	global_store_dwordx2 v[8:9], v[4:5], off offset:192
	v_mov_b32_e32 v10, v234
	v_mov_b32_e32 v11, v235
	s_nop 0
	global_load_dwordx4 v[4:7], v68, s[30:31] offset:448
	v_lshlrev_b32_e32 v13, 16, v10
	v_and_b32_e32 v10, 0xffff0000, v10
	v_lshlrev_b32_e32 v14, 16, v11
	v_and_b32_e32 v11, 0xffff0000, v11
	v_mul_f32_e32 v13, 0xbfb8aa3b, v13
	v_mul_f32_e32 v10, 0xbfb8aa3b, v10
	v_mul_f32_e32 v14, 0xbfb8aa3b, v14
	v_mul_f32_e32 v11, 0xbfb8aa3b, v11
	v_exp_f32_e32 v13, v13
	v_exp_f32_e32 v10, v10
	v_exp_f32_e32 v14, v14
	v_exp_f32_e32 v11, v11
	v_add_f32_e32 v13, 1.0, v13
	v_add_f32_e32 v16, 1.0, v10
	v_add_f32_e32 v14, 1.0, v14
	v_add_f32_e32 v11, 1.0, v11
	v_rcp_f32_e32 v10, v13
	v_rcp_f32_e32 v14, v14
	v_rcp_f32_e32 v15, v11
	v_rcp_f32_e32 v11, v16
	v_pk_mul_f32 v[2:3], v[2:3], v[14:15]
	v_pk_mul_f32 v[0:1], v[0:1], v[10:11]
	v_pk_mul_f32 v[2:3], v[12:13], v[2:3] op_sel_hi:[0,1]
	v_pk_mul_f32 v[0:1], v[12:13], v[0:1] op_sel_hi:[0,1]
	s_waitcnt vmcnt(0)
	v_pk_mul_f32 v[2:3], v[6:7], v[2:3]
	v_pk_mul_f32 v[0:1], v[4:5], v[0:1]
	s_nop 0
	v_cvt_pk_bf16_f32 v0, v0, v1
	v_cvt_pk_bf16_f32 v1, v2, v3
	global_store_dwordx2 v[8:9], v[0:1], off offset:224
	s_cbranch_scc1 .LBB1_806

.LBB1_130:
	s_or_b64 exec, exec, s[30:31]
	v_lshlrev_b32_e32 v191, 3, v92
	s_lshl_b32 s57, s2, 7
	v_lshlrev_b32_e32 v48, 2, v191
	s_add_i32 s2, 16, 0x13000
	v_add_u32_e32 v49, s2, v48
	s_add_i32 s4, 16, 0x13200
	v_add_u32_e32 v50, s4, v48
	s_waitcnt vmcnt(0)
	ds_read_b128 v[32:35], v49
	ds_read_b128 v[36:39], v50
	v_lshlrev_b32_e32 v40, 16, v28
	v_cmp_lt_i32_e32 vcc, v171, v169
	v_lshl_add_u32 v158, v92, 4, 16
	s_waitcnt lgkmcnt(1)
	v_fma_f32 v51, v32, v40, 0
	v_and_b32_e32 v32, 0xffff0000, v28
	v_fmac_f32_e32 v51, v33, v32
	v_or_b32_e32 v33, 16, v48
	v_add_u32_e32 v53, s2, v33
	s_waitcnt lgkmcnt(0)
	v_fma_f32 v52, v36, v40, 0
	v_add_u32_e32 v54, s4, v33
	ds_read_b128 v[40:43], v53
	ds_read_b128 v[44:47], v54
	v_fmac_f32_e32 v52, v37, v32
	v_lshlrev_b32_e32 v32, 16, v29
	v_fmac_f32_e32 v51, v34, v32
	v_fmac_f32_e32 v52, v38, v32
	v_and_b32_e32 v32, 0xffff0000, v29
	v_fmac_f32_e32 v51, v35, v32
	v_fmac_f32_e32 v52, v39, v32
	v_lshlrev_b32_e32 v32, 16, v30
	s_waitcnt lgkmcnt(1)
	v_fmac_f32_e32 v51, v40, v32
	s_waitcnt lgkmcnt(0)
	v_fmac_f32_e32 v52, v44, v32
	v_and_b32_e32 v32, 0xffff0000, v30
	v_fmac_f32_e32 v51, v41, v32
	v_fmac_f32_e32 v52, v45, v32
	v_lshlrev_b32_e32 v32, 16, v31
	v_fmac_f32_e32 v51, v42, v32
	v_fmac_f32_e32 v52, v46, v32
	v_or_b32_e32 v32, 0x80, v48
	v_add_u32_e32 v55, s2, v32
	v_add_u32_e32 v56, s4, v32
	ds_read_b128 v[32:35], v55
	ds_read_b128 v[36:39], v56
	v_and_b32_e32 v40, 0xffff0000, v31
	v_fmac_f32_e32 v51, v43, v40
	v_fmac_f32_e32 v52, v47, v40
	v_lshlrev_b32_e32 v40, 16, v20
	s_waitcnt lgkmcnt(1)
	v_fmac_f32_e32 v51, v32, v40
	v_and_b32_e32 v32, 0xffff0000, v20
	v_fmac_f32_e32 v51, v33, v32
	v_or_b32_e32 v33, 0x90, v48
	v_add_u32_e32 v57, s2, v33
	s_waitcnt lgkmcnt(0)
	v_fmac_f32_e32 v52, v36, v40
	v_add_u32_e32 v58, s4, v33
	ds_read_b128 v[40:43], v57
	ds_read_b128 v[44:47], v58
	v_fmac_f32_e32 v52, v37, v32
	v_lshlrev_b32_e32 v32, 16, v21
	v_fmac_f32_e32 v51, v34, v32
	v_fmac_f32_e32 v52, v38, v32
	v_and_b32_e32 v32, 0xffff0000, v21
	v_fmac_f32_e32 v51, v35, v32
	v_fmac_f32_e32 v52, v39, v32
	v_lshlrev_b32_e32 v32, 16, v22
	s_waitcnt lgkmcnt(1)
	v_fmac_f32_e32 v51, v40, v32
	s_waitcnt lgkmcnt(0)
	v_fmac_f32_e32 v52, v44, v32
	v_and_b32_e32 v32, 0xffff0000, v22
	v_fmac_f32_e32 v51, v41, v32
	v_fmac_f32_e32 v52, v45, v32
	v_lshlrev_b32_e32 v32, 16, v23
	v_fmac_f32_e32 v51, v42, v32
	v_fmac_f32_e32 v52, v46, v32
	v_or_b32_e32 v32, 0x100, v48
	v_add_u32_e32 v59, s2, v32
	v_add_u32_e32 v60, s4, v32
	ds_read_b128 v[32:35], v59
	ds_read_b128 v[36:39], v60
	v_and_b32_e32 v40, 0xffff0000, v23
	v_fmac_f32_e32 v51, v43, v40
	v_fmac_f32_e32 v52, v47, v40
	v_lshlrev_b32_e32 v40, 16, v12
	s_waitcnt lgkmcnt(1)
	v_fmac_f32_e32 v51, v32, v40
	v_and_b32_e32 v32, 0xffff0000, v12
	v_fmac_f32_e32 v51, v33, v32
	v_or_b32_e32 v33, 0x110, v48
	v_add_u32_e32 v61, s2, v33
	s_waitcnt lgkmcnt(0)
	v_fmac_f32_e32 v52, v36, v40
	v_add_u32_e32 v62, s4, v33
	ds_read_b128 v[40:43], v61
	ds_read_b128 v[44:47], v62
	v_fmac_f32_e32 v52, v37, v32
	v_lshlrev_b32_e32 v32, 16, v13
	v_fmac_f32_e32 v51, v34, v32
	v_fmac_f32_e32 v52, v38, v32
	v_and_b32_e32 v32, 0xffff0000, v13
	v_fmac_f32_e32 v51, v35, v32
	v_fmac_f32_e32 v52, v39, v32
	v_lshlrev_b32_e32 v32, 16, v14
	s_waitcnt lgkmcnt(1)
	v_fmac_f32_e32 v51, v40, v32
	s_waitcnt lgkmcnt(0)
	v_fmac_f32_e32 v52, v44, v32
	v_and_b32_e32 v32, 0xffff0000, v14
	v_fmac_f32_e32 v51, v41, v32
	v_fmac_f32_e32 v52, v45, v32
	v_lshlrev_b32_e32 v32, 16, v15
	v_fmac_f32_e32 v51, v42, v32
	v_fmac_f32_e32 v52, v46, v32
	v_or_b32_e32 v32, 0x180, v48
	v_add_u32_e32 v63, s2, v32
	v_add_u32_e32 v64, s4, v32
	ds_read_b128 v[32:35], v63
	ds_read_b128 v[36:39], v64
	v_and_b32_e32 v40, 0xffff0000, v15
	v_fmac_f32_e32 v51, v43, v40
	v_fmac_f32_e32 v52, v47, v40
	v_lshlrev_b32_e32 v40, 16, v4
	s_waitcnt lgkmcnt(1)
	v_fmac_f32_e32 v51, v32, v40
	v_and_b32_e32 v32, 0xffff0000, v4
	v_fmac_f32_e32 v51, v33, v32
	v_or_b32_e32 v33, 0x190, v48
	v_add_u32_e32 v48, s2, v33
	s_waitcnt lgkmcnt(0)
	v_fmac_f32_e32 v52, v36, v40
	v_add_u32_e32 v65, s4, v33
	ds_read_b128 v[40:43], v48
	ds_read_b128 v[44:47], v65
	v_fmac_f32_e32 v52, v37, v32
	v_lshlrev_b32_e32 v32, 16, v5
	v_fmac_f32_e32 v51, v34, v32
	v_fmac_f32_e32 v52, v38, v32
	v_and_b32_e32 v32, 0xffff0000, v5
	v_fmac_f32_e32 v51, v35, v32
	v_fmac_f32_e32 v52, v39, v32
	v_lshlrev_b32_e32 v32, 16, v6
	s_waitcnt lgkmcnt(1)
	v_fmac_f32_e32 v51, v40, v32
	s_waitcnt lgkmcnt(0)
	v_fmac_f32_e32 v52, v44, v32
	v_and_b32_e32 v32, 0xffff0000, v6
	v_fmac_f32_e32 v51, v41, v32
	v_lshlrev_b32_e32 v33, 16, v7
	v_fmac_f32_e32 v51, v42, v33
	v_and_b32_e32 v34, 0xffff0000, v7
	v_cndmask_b32_e32 v35, v168, v171, vcc
	v_fmac_f32_e32 v51, v43, v34
	v_lshlrev_b32_e32 v109, 2, v35
	ds_bpermute_b32 v35, v109, v51
	v_fmac_f32_e32 v52, v45, v32
	v_fmac_f32_e32 v52, v46, v33
	v_fmac_f32_e32 v52, v47, v34
	v_cmp_lt_i32_e32 vcc, v170, v169
	ds_bpermute_b32 v40, v109, v52
	s_waitcnt lgkmcnt(1)
	v_add_f32_e32 v192, v51, v35
	v_cndmask_b32_e32 v32, v168, v170, vcc
	v_lshlrev_b32_e32 v154, 2, v32
	ds_read_b128 v[32:35], v49
	ds_read_b128 v[36:39], v50
	s_waitcnt lgkmcnt(2)
	v_add_f32_e32 v194, v52, v40
	v_lshlrev_b32_e32 v40, 16, v24
	v_mad_u32_u24 v157, v155, s3, v158
	s_waitcnt lgkmcnt(1)
	v_fma_f32 v49, v32, v40, 0
	s_waitcnt lgkmcnt(0)
	v_fma_f32 v50, v36, v40, 0
	ds_read_b128 v[40:43], v53
	ds_read_b128 v[44:47], v54
	v_and_b32_e32 v32, 0xffff0000, v24
	v_fmac_f32_e32 v49, v33, v32
	v_fmac_f32_e32 v50, v37, v32
	v_lshlrev_b32_e32 v32, 16, v25
	v_fmac_f32_e32 v49, v34, v32
	v_fmac_f32_e32 v50, v38, v32
	v_and_b32_e32 v32, 0xffff0000, v25
	v_fmac_f32_e32 v49, v35, v32
	v_fmac_f32_e32 v50, v39, v32
	v_lshlrev_b32_e32 v32, 16, v26
	s_waitcnt lgkmcnt(1)
	v_fmac_f32_e32 v49, v40, v32
	s_waitcnt lgkmcnt(0)
	v_fmac_f32_e32 v50, v44, v32
	v_and_b32_e32 v32, 0xffff0000, v26
	v_fmac_f32_e32 v49, v41, v32
	v_fmac_f32_e32 v50, v45, v32
	v_lshlrev_b32_e32 v32, 16, v27
	v_fmac_f32_e32 v49, v42, v32
	v_fmac_f32_e32 v50, v46, v32
	ds_read_b128 v[32:35], v55
	ds_read_b128 v[36:39], v56
	v_and_b32_e32 v40, 0xffff0000, v27
	v_fmac_f32_e32 v49, v43, v40
	v_fmac_f32_e32 v50, v47, v40
	v_lshlrev_b32_e32 v40, 16, v16
	s_waitcnt lgkmcnt(1)
	v_fmac_f32_e32 v49, v32, v40
	s_waitcnt lgkmcnt(0)
	v_fmac_f32_e32 v50, v36, v40
	ds_read_b128 v[40:43], v57
	ds_read_b128 v[44:47], v58
	v_and_b32_e32 v32, 0xffff0000, v16
	v_fmac_f32_e32 v49, v33, v32
	v_fmac_f32_e32 v50, v37, v32
	v_lshlrev_b32_e32 v32, 16, v17
	v_fmac_f32_e32 v49, v34, v32
	v_fmac_f32_e32 v50, v38, v32
	v_and_b32_e32 v32, 0xffff0000, v17
	v_fmac_f32_e32 v49, v35, v32
	v_fmac_f32_e32 v50, v39, v32
	v_lshlrev_b32_e32 v32, 16, v18
	s_waitcnt lgkmcnt(1)
	v_fmac_f32_e32 v49, v40, v32
	s_waitcnt lgkmcnt(0)
	v_fmac_f32_e32 v50, v44, v32
	v_and_b32_e32 v32, 0xffff0000, v18
	v_fmac_f32_e32 v49, v41, v32
	v_fmac_f32_e32 v50, v45, v32
	v_lshlrev_b32_e32 v32, 16, v19
	v_fmac_f32_e32 v49, v42, v32
	v_fmac_f32_e32 v50, v46, v32
	ds_read_b128 v[32:35], v59
	ds_read_b128 v[36:39], v60
	v_and_b32_e32 v40, 0xffff0000, v19
	v_fmac_f32_e32 v49, v43, v40
	v_fmac_f32_e32 v50, v47, v40
	v_lshlrev_b32_e32 v40, 16, v8
	s_waitcnt lgkmcnt(1)
	v_fmac_f32_e32 v49, v32, v40
	s_waitcnt lgkmcnt(0)
	v_fmac_f32_e32 v50, v36, v40
	ds_read_b128 v[40:43], v61
	ds_read_b128 v[44:47], v62
	v_and_b32_e32 v32, 0xffff0000, v8
	v_fmac_f32_e32 v49, v33, v32
	v_fmac_f32_e32 v50, v37, v32
	v_lshlrev_b32_e32 v32, 16, v9
	v_fmac_f32_e32 v49, v34, v32
	v_fmac_f32_e32 v50, v38, v32
	v_and_b32_e32 v32, 0xffff0000, v9
	v_fmac_f32_e32 v49, v35, v32
	v_fmac_f32_e32 v50, v39, v32
	v_lshlrev_b32_e32 v32, 16, v10
	s_waitcnt lgkmcnt(1)
	v_fmac_f32_e32 v49, v40, v32
	s_waitcnt lgkmcnt(0)
	v_fmac_f32_e32 v50, v44, v32
	v_and_b32_e32 v32, 0xffff0000, v10
	v_fmac_f32_e32 v49, v41, v32
	v_fmac_f32_e32 v50, v45, v32
	v_lshlrev_b32_e32 v32, 16, v11
	v_fmac_f32_e32 v49, v42, v32
	v_fmac_f32_e32 v50, v46, v32
	ds_read_b128 v[32:35], v63
	ds_read_b128 v[36:39], v64
	v_and_b32_e32 v40, 0xffff0000, v11
	v_fmac_f32_e32 v49, v43, v40
	v_fmac_f32_e32 v50, v47, v40
	v_lshlrev_b32_e32 v40, 16, v0
	s_waitcnt lgkmcnt(1)
	v_fmac_f32_e32 v49, v32, v40
	s_waitcnt lgkmcnt(0)
	v_fmac_f32_e32 v50, v36, v40
	ds_read_b128 v[40:43], v48
	ds_read_b128 v[44:47], v65
	v_and_b32_e32 v32, 0xffff0000, v0
	v_fmac_f32_e32 v49, v33, v32
	v_fmac_f32_e32 v50, v37, v32
	v_lshlrev_b32_e32 v32, 16, v1
	v_fmac_f32_e32 v49, v34, v32
	v_fmac_f32_e32 v50, v38, v32
	v_and_b32_e32 v32, 0xffff0000, v1
	v_fmac_f32_e32 v49, v35, v32
	v_fmac_f32_e32 v50, v39, v32
	v_lshlrev_b32_e32 v32, 16, v2
	s_waitcnt lgkmcnt(1)
	v_fmac_f32_e32 v49, v40, v32
	s_waitcnt lgkmcnt(0)
	v_fmac_f32_e32 v50, v44, v32
	v_and_b32_e32 v32, 0xffff0000, v2
	v_fmac_f32_e32 v49, v41, v32
	v_fmac_f32_e32 v50, v45, v32
	v_lshlrev_b32_e32 v32, 16, v3
	v_fmac_f32_e32 v49, v42, v32
	v_fmac_f32_e32 v50, v46, v32
	v_and_b32_e32 v32, 0xffff0000, v3
	v_fmac_f32_e32 v49, v43, v32
	v_fmac_f32_e32 v50, v47, v32
	ds_bpermute_b32 v33, v109, v49
	ds_bpermute_b32 v32, v109, v50
	ds_bpermute_b32 v193, v154, v192
	ds_bpermute_b32 v195, v154, v194
	s_waitcnt lgkmcnt(3)
	v_add_f32_e32 v159, v49, v33
	s_waitcnt lgkmcnt(2)
	v_add_f32_e32 v161, v50, v32
	ds_read_b128 v[32:35], v157
	ds_read_b128 v[36:39], v157 offset:4352
	ds_read_b128 v[40:43], v157 offset:8704
	ds_read_b128 v[44:47], v157 offset:13056
	ds_read_b128 v[48:51], v157 offset:17408
	ds_read_b128 v[52:55], v157 offset:21760
	ds_read_b128 v[56:59], v157 offset:26112
	ds_read_b128 v[60:63], v157 offset:30464
	ds_bpermute_b32 v160, v154, v159
	ds_bpermute_b32 v188, v154, v161
	s_setprio 2
	s_waitcnt lgkmcnt(9)
	v_mfma_f32_16x16x32_bf16 v[64:67], v[32:35], v[28:31], 0
	v_mfma_f32_16x16x32_bf16 v[32:35], v[32:35], v[24:27], 0
	s_waitcnt lgkmcnt(8)
	v_mfma_f32_16x16x32_bf16 v[68:71], v[36:39], v[28:31], 0
	v_mfma_f32_16x16x32_bf16 v[36:39], v[36:39], v[24:27], 0
	s_waitcnt lgkmcnt(7)
	v_mfma_f32_16x16x32_bf16 v[72:75], v[40:43], v[28:31], 0
	v_mfma_f32_16x16x32_bf16 v[40:43], v[40:43], v[24:27], 0
	s_waitcnt lgkmcnt(6)
	v_mfma_f32_16x16x32_bf16 v[76:79], v[44:47], v[28:31], 0
	v_mfma_f32_16x16x32_bf16 v[44:47], v[44:47], v[24:27], 0
	s_waitcnt lgkmcnt(5)
	v_mfma_f32_16x16x32_bf16 v[80:83], v[48:51], v[28:31], 0
	v_mfma_f32_16x16x32_bf16 v[48:51], v[48:51], v[24:27], 0
	s_waitcnt lgkmcnt(4)
	v_mfma_f32_16x16x32_bf16 v[84:87], v[52:55], v[28:31], 0
	v_mfma_f32_16x16x32_bf16 v[52:55], v[52:55], v[24:27], 0
	s_waitcnt lgkmcnt(3)
	v_mfma_f32_16x16x32_bf16 v[88:91], v[56:59], v[28:31], 0
	v_mfma_f32_16x16x32_bf16 v[56:59], v[56:59], v[24:27], 0
	s_waitcnt lgkmcnt(2)
	v_mfma_f32_16x16x32_bf16 v[94:97], v[60:63], v[28:31], 0
	v_mfma_f32_16x16x32_bf16 v[60:63], v[60:63], v[24:27], 0
	s_setprio 1
	ds_read_b128 v[98:101], v157 offset:64
	ds_read_b128 v[110:113], v157 offset:4416
	ds_read_b128 v[114:117], v157 offset:8768
	ds_read_b128 v[118:121], v157 offset:13120
	ds_read_b128 v[122:125], v157 offset:17472
	ds_read_b128 v[130:133], v157 offset:21824
	ds_read_b128 v[134:137], v157 offset:26176
	ds_read_b128 v[138:141], v157 offset:30528
	s_setprio 2
	s_waitcnt lgkmcnt(7)
	v_mfma_f32_16x16x32_bf16 v[64:67], v[98:101], v[20:23], v[64:67]
	v_mfma_f32_16x16x32_bf16 v[32:35], v[98:101], v[16:19], v[32:35]
	s_waitcnt lgkmcnt(6)
	v_mfma_f32_16x16x32_bf16 v[68:71], v[110:113], v[20:23], v[68:71]
	v_mfma_f32_16x16x32_bf16 v[36:39], v[110:113], v[16:19], v[36:39]
	s_waitcnt lgkmcnt(5)
	v_mfma_f32_16x16x32_bf16 v[72:75], v[114:117], v[20:23], v[72:75]
	v_mfma_f32_16x16x32_bf16 v[40:43], v[114:117], v[16:19], v[40:43]
	s_waitcnt lgkmcnt(4)
	v_mfma_f32_16x16x32_bf16 v[76:79], v[118:121], v[20:23], v[76:79]
	v_mfma_f32_16x16x32_bf16 v[44:47], v[118:121], v[16:19], v[44:47]
	s_waitcnt lgkmcnt(3)
	v_mfma_f32_16x16x32_bf16 v[80:83], v[122:125], v[20:23], v[80:83]
	v_mfma_f32_16x16x32_bf16 v[48:51], v[122:125], v[16:19], v[48:51]
	s_waitcnt lgkmcnt(2)
	v_mfma_f32_16x16x32_bf16 v[84:87], v[130:133], v[20:23], v[84:87]
	v_mfma_f32_16x16x32_bf16 v[52:55], v[130:133], v[16:19], v[52:55]
	s_waitcnt lgkmcnt(1)
	v_mfma_f32_16x16x32_bf16 v[88:91], v[134:137], v[20:23], v[88:91]
	v_mfma_f32_16x16x32_bf16 v[56:59], v[134:137], v[16:19], v[56:59]
	s_waitcnt lgkmcnt(0)
	v_mfma_f32_16x16x32_bf16 v[94:97], v[138:141], v[20:23], v[94:97]
	v_mfma_f32_16x16x32_bf16 v[60:63], v[138:141], v[16:19], v[60:63]
	s_setprio 1
	ds_read_b128 v[98:101], v157 offset:128
	ds_read_b128 v[110:113], v157 offset:4480
	ds_read_b128 v[114:117], v157 offset:8832
	ds_read_b128 v[118:121], v157 offset:13184
	ds_read_b128 v[122:125], v157 offset:17536
	ds_read_b128 v[130:133], v157 offset:21888
	ds_read_b128 v[134:137], v157 offset:26240
	ds_read_b128 v[138:141], v157 offset:30592
	s_setprio 2
	s_waitcnt lgkmcnt(7)
	v_mfma_f32_16x16x32_bf16 v[64:67], v[98:101], v[12:15], v[64:67]
	v_mfma_f32_16x16x32_bf16 v[32:35], v[98:101], v[8:11], v[32:35]
	s_waitcnt lgkmcnt(6)
	v_mfma_f32_16x16x32_bf16 v[68:71], v[110:113], v[12:15], v[68:71]
	v_mfma_f32_16x16x32_bf16 v[36:39], v[110:113], v[8:11], v[36:39]
	s_waitcnt lgkmcnt(5)
	v_mfma_f32_16x16x32_bf16 v[72:75], v[114:117], v[12:15], v[72:75]
	v_mfma_f32_16x16x32_bf16 v[40:43], v[114:117], v[8:11], v[40:43]
	s_waitcnt lgkmcnt(4)
	v_mfma_f32_16x16x32_bf16 v[100:103], v[118:121], v[12:15], v[76:79]
	v_mfma_f32_16x16x32_bf16 v[44:47], v[118:121], v[8:11], v[44:47]
	s_waitcnt lgkmcnt(3)
	v_mfma_f32_16x16x32_bf16 v[110:113], v[122:125], v[12:15], v[80:83]
	v_mfma_f32_16x16x32_bf16 v[48:51], v[122:125], v[8:11], v[48:51]
	s_waitcnt lgkmcnt(2)
	v_mfma_f32_16x16x32_bf16 v[114:117], v[130:133], v[12:15], v[84:87]
	v_mfma_f32_16x16x32_bf16 v[118:121], v[130:133], v[8:11], v[52:55]
	s_waitcnt lgkmcnt(1)
	v_mfma_f32_16x16x32_bf16 v[122:125], v[134:137], v[12:15], v[88:91]
	v_mfma_f32_16x16x32_bf16 v[130:133], v[134:137], v[8:11], v[56:59]
	s_waitcnt lgkmcnt(0)
	v_mfma_f32_16x16x32_bf16 v[134:137], v[138:141], v[12:15], v[94:97]
	v_mfma_f32_16x16x32_bf16 v[138:141], v[138:141], v[8:11], v[60:63]
	s_setprio 1
	ds_read_b128 v[52:55], v157 offset:192
	ds_read_b128 v[56:59], v157 offset:4544
	ds_read_b128 v[60:63], v157 offset:8896
	ds_read_b128 v[142:145], v157 offset:13248
	ds_read_b128 v[146:149], v157 offset:17600
	ds_read_b128 v[150:153], v157 offset:21952
	ds_read_b128 v[196:199], v157 offset:26304
	ds_read_b128 v[200:203], v157 offset:30656
	s_setprio 2
	s_waitcnt lgkmcnt(7)
	v_mfma_f32_16x16x32_bf16 v[96:99], v[52:55], v[4:7], v[64:67]
	v_mfma_f32_16x16x32_bf16 v[88:91], v[52:55], v[0:3], v[32:35]
	s_waitcnt lgkmcnt(6)
	v_mfma_f32_16x16x32_bf16 v[84:87], v[56:59], v[4:7], v[68:71]
	v_mfma_f32_16x16x32_bf16 v[80:83], v[56:59], v[0:3], v[36:39]
	s_waitcnt lgkmcnt(5)
	v_mfma_f32_16x16x32_bf16 v[76:79], v[60:63], v[4:7], v[72:75]
	v_mfma_f32_16x16x32_bf16 v[72:75], v[60:63], v[0:3], v[40:43]
	s_waitcnt lgkmcnt(4)
	v_mfma_f32_16x16x32_bf16 v[68:71], v[142:145], v[4:7], v[100:103]
	v_mfma_f32_16x16x32_bf16 v[64:67], v[142:145], v[0:3], v[44:47]
	s_waitcnt lgkmcnt(3)
	v_mfma_f32_16x16x32_bf16 v[60:63], v[146:149], v[4:7], v[110:113]
	v_mfma_f32_16x16x32_bf16 v[56:59], v[146:149], v[0:3], v[48:51]
	s_waitcnt lgkmcnt(2)
	v_mfma_f32_16x16x32_bf16 v[52:55], v[150:153], v[4:7], v[114:117]
	v_mfma_f32_16x16x32_bf16 v[48:51], v[150:153], v[0:3], v[118:121]
	s_waitcnt lgkmcnt(1)
	v_mfma_f32_16x16x32_bf16 v[44:47], v[196:199], v[4:7], v[122:125]
	v_mfma_f32_16x16x32_bf16 v[40:43], v[196:199], v[0:3], v[130:133]
	s_waitcnt lgkmcnt(0)
	v_mfma_f32_16x16x32_bf16 v[36:39], v[200:203], v[4:7], v[134:137]
	v_mfma_f32_16x16x32_bf16 v[32:35], v[200:203], v[0:3], v[138:141]
	s_setprio 1
	v_readfirstlane_b32 s2, v93
	v_lshlrev_b32_e32 v93, 2, v108
	s_add_i32 s4, 16, 0x11800
	s_add_i32 s5, 16, 0x12000
	v_add_u32_e32 v94, s4, v93
	v_add_u32_e32 v95, s5, v93
	s_add_i32 s6, 16, 0x11a00
	s_add_i32 s7, 16, 0x12200
	s_barrier
	ds_read_b32 v94, v94
	ds_read_b32 v196, v95
	v_add_u32_e32 v95, s6, v93
	v_add_u32_e32 v93, s7, v93
	v_add_u32_e32 v200, 0x11e00, v158
	ds_read_b32 v95, v95
	ds_read_b128 v[100:103], v200
	ds_read_b32 v197, v93
	v_lshlrev_b32_e32 v93, 2, v106
	s_waitcnt lgkmcnt(3)
	v_sub_f32_e32 v198, v94, v196
	v_add_u32_e32 v94, s4, v93
	v_add_u32_e32 v111, s6, v93
	v_add_u32_e32 v190, s5, v93
	ds_read_b32 v110, v94
	ds_read_b32 v112, v111
	s_waitcnt lgkmcnt(2)
	v_sub_f32_e32 v199, v95, v197
	v_add_u32_e32 v189, s7, v93
	v_lshlrev_b32_e32 v156, 2, v92
	v_add_u32_e32 v201, 0x11c00, v158
	ds_read_b32 v111, v190
	ds_read_b32 v113, v189
	ds_read_b128 v[92:95], v201
	s_cmp_lt_i32 s2, 1
	s_cselect_b64 s[30:31], -1, 0
	s_mov_b64 s[38:39], -1
	s_and_b64 vcc, exec, s[30:31]
	s_cbranch_vccz .LBB1_158
	s_cmp_eq_u32 s2, 0
	v_add_f32_e32 v123, v199, v100
	v_add_f32_e32 v121, v199, v101
	v_add_f32_e32 v122, v199, v102
	v_add_f32_e32 v119, v199, v103
	s_cbranch_scc1 .LBB1_196
	v_mul_f32_e32 v114, 0x3fb8aa3b, v123
	v_mul_f32_e32 v115, 0x3fb8aa3b, v121
	v_exp_f32_e32 v114, v114
	v_exp_f32_e32 v115, v115
	v_mul_f32_e32 v116, 0x3fb8aa3b, v122
	v_mul_f32_e32 v117, 0x3fb8aa3b, v119
	v_exp_f32_e32 v116, v116
	v_exp_f32_e32 v117, v117
	v_pk_mul_f32 v[114:115], v[96:97], v[114:115]
	s_nop 0
	v_add_f32_e32 v118, 0, v114
	v_add_f32_e32 v118, v115, v118
	v_pk_mul_f32 v[116:117], v[98:99], v[116:117]
	v_mov_b32_e32 v120, v115
	v_add_f32_e32 v118, v116, v118
	v_add_f32_e32 v134, v117, v118
	v_mov_b32_e32 v118, v117
	s_cbranch_execnz .LBB1_197

.LBB1_806:
	s_setprio 0
	s_mov_b32 s59, 0
	v_readlane_b32 s2, v242, 62
	s_cmp_ge_i32 s56, s2
	s_cselect_b64 s[4:5], -1, 0
	s_sub_i32 s2, s56, s2
	s_load_dwordx2 s[56:57], s[0:1], 0x1b8
	s_load_dwordx16 s[64:79], s[0:1], 0x100
	s_cmpk_lt_i32 s2, 0x580
	s_cselect_b64 s[6:7], -1, 0
	s_and_b64 s[4:5], s[4:5], s[6:7]
	v_readlane_b32 s14, v241, 36
	s_andn2_b64 vcc, exec, s[4:5]
	v_readlane_b32 s15, v241, 37
	s_cbranch_vccnz .LBB1_810
